# GEMM tiles: dropped the first workgroup barrier of every tile prologue (buffer 0 is not read after the previous tile's mid barrier); s_nop padding re-checked
# baseline (speedup 1.0000x reference)
.LBB0_83:
	s_lshl_b32 s2, s25, 7
	s_ashr_i32 s3, s2, 31
	v_lshl_add_u64 v[0:1], s[2:3], 2, v[132:133]
	s_mov_b32 s3, 0xa000
	v_add_co_u32_e32 v2, vcc, s3, v0
	s_mov_b32 s3, 0x14000
	s_nop 0
	v_addc_co_u32_e32 v3, vcc, 0, v1, vcc
	v_add_co_u32_e32 v4, vcc, s3, v0
	s_mov_b32 s3, 0x28000
	s_nop 0
	v_addc_co_u32_e32 v5, vcc, 0, v1, vcc
	v_add_co_u32_e32 v6, vcc, s12, v0
	s_nop 1
	v_addc_co_u32_e32 v7, vcc, 0, v1, vcc
	v_add_co_u32_e32 v8, vcc, s3, v0
	s_mov_b32 s3, 0x32000
	s_nop 0
	v_addc_co_u32_e32 v9, vcc, 0, v1, vcc
	v_add_co_u32_e32 v10, vcc, s3, v0
	s_mov_b32 s3, 0x46000
	s_nop 0
	v_addc_co_u32_e32 v11, vcc, 0, v1, vcc
	v_add_co_u32_e32 v12, vcc, s63, v0
	s_nop 0
	s_nop 0
	v_addc_co_u32_e32 v13, vcc, 0, v1, vcc
	v_add_co_u32_e32 v14, vcc, s3, v0
	s_mov_b32 s3, 0x50000
	s_nop 0
	v_addc_co_u32_e32 v15, vcc, 0, v1, vcc
	global_load_dword v128, v[0:1], off
	global_load_dword v157, v[2:3], off
	global_load_dword v158, v[4:5], off
	global_load_dword v159, v[6:7], off
	global_load_dword v160, v[8:9], off
	global_load_dword v161, v[10:11], off
	global_load_dword v162, v[12:13], off
	global_load_dword v163, v[14:15], off
	v_add_co_u32_e32 v2, vcc, s3, v0
	s_mov_b32 s3, 0x64000
	s_nop 0
	v_addc_co_u32_e32 v3, vcc, 0, v1, vcc
	v_add_co_u32_e32 v4, vcc, s57, v0
	s_lshl_b32 s27, s24, 7
	s_nop 0
	v_addc_co_u32_e32 v5, vcc, 0, v1, vcc
	v_add_co_u32_e32 v6, vcc, s3, v0
	s_mov_b32 s3, 0x6e000
	s_nop 0
	v_addc_co_u32_e32 v7, vcc, 0, v1, vcc
	v_add_co_u32_e32 v8, vcc, s3, v0
	s_mov_b32 s3, 0x82000
	s_nop 0
	v_addc_co_u32_e32 v9, vcc, 0, v1, vcc
	v_add_co_u32_e32 v10, vcc, s62, v0
	s_mov_b32 s24, -2
	s_nop 0
	v_addc_co_u32_e32 v11, vcc, 0, v1, vcc
	v_add_co_u32_e32 v12, vcc, s3, v0
	s_mov_b32 s3, 0x8c000
	s_nop 0
	v_addc_co_u32_e32 v13, vcc, 0, v1, vcc
	v_add_co_u32_e32 v14, vcc, s3, v0
	s_nop 1
	v_addc_co_u32_e32 v15, vcc, 0, v1, vcc
	v_add_co_u32_e32 v0, vcc, s65, v0
	s_nop 1
	v_addc_co_u32_e32 v1, vcc, 0, v1, vcc
	global_load_dword v164, v[2:3], off
	global_load_dword v165, v[4:5], off
	global_load_dword v168, v[6:7], off
	global_load_dword v175, v[8:9], off
	global_load_dword v179, v[10:11], off
	global_load_dword v183, v[12:13], off
	global_load_dword v190, v[14:15], off
	global_load_dword v191, v[0:1], off
	v_add_u32_e32 v0, s2, v130
	v_ashrrev_i32_e32 v1, 31, v0
	v_lshlrev_b64 v[0:1], 11, v[0:1]
	v_lshl_add_u64 v[138:139], v[134:135], 0, v[0:1]
	v_add_u32_e32 v0, s27, v130
	v_ashrrev_i32_e32 v1, 31, v0
	v_lshlrev_b64 v[0:1], 11, v[0:1]
	v_lshl_add_u64 v[140:141], v[136:137], 0, v[0:1]
	v_add_co_u32_e32 v0, vcc, s11, v138
	s_nop 1
	v_addc_co_u32_e32 v1, vcc, 0, v139, vcc
	v_add_co_u32_e32 v2, vcc, s33, v138
	s_nop 1
	v_addc_co_u32_e32 v3, vcc, 0, v139, vcc
	global_load_dwordx4 v[100:103], v[0:1], off offset:128
	global_load_dwordx4 v[104:107], v[2:3], off offset:128
	v_add_co_u32_e32 v0, vcc, 0x30000, v138
	global_load_dwordx4 v[96:99], v[138:139], off offset:128
	global_load_dwordx4 v[108:111], v[140:141], off offset:128
	v_addc_co_u32_e32 v1, vcc, 0, v139, vcc
	v_add_co_u32_e32 v2, vcc, s11, v140
	s_nop 1
	v_addc_co_u32_e32 v3, vcc, 0, v141, vcc
	global_load_dwordx4 v[112:115], v[0:1], off offset:128
	global_load_dwordx4 v[116:119], v[2:3], off offset:128
	v_add_co_u32_e32 v0, vcc, 0x20000, v140
	s_nop 1
	v_addc_co_u32_e32 v1, vcc, 0, v141, vcc
	v_add_co_u32_e32 v2, vcc, 0x30000, v140
	s_nop 1
	v_addc_co_u32_e32 v3, vcc, 0, v141, vcc
	global_load_dwordx4 v[120:123], v[0:1], off offset:128
	global_load_dwordx4 v[124:127], v[2:3], off offset:128
	v_mov_b32_e32 v0, 0
	v_mov_b32_e32 v1, v0
	v_mov_b32_e32 v2, v0
	v_mov_b32_e32 v3, v0
	v_mov_b32_e32 v4, v0
	v_mov_b32_e32 v5, v0
	v_mov_b32_e32 v6, v0
	v_mov_b32_e32 v7, v0
	v_mov_b32_e32 v8, v0
	v_mov_b32_e32 v9, v0
	v_mov_b32_e32 v10, v0
	v_mov_b32_e32 v11, v0
	v_mov_b32_e32 v12, v0
	v_mov_b32_e32 v13, v0
	v_mov_b32_e32 v14, v0
	v_mov_b32_e32 v15, v0
	v_mov_b32_e32 v16, v0
	v_mov_b32_e32 v17, v0
	v_mov_b32_e32 v18, v0
	v_mov_b32_e32 v19, v0
	s_waitcnt vmcnt(40)
	v_mov_b32_e32 v20, v0
	v_mov_b32_e32 v21, v0
	v_mov_b32_e32 v22, v0
	v_mov_b32_e32 v23, v0
	v_mov_b32_e32 v24, v0
	v_mov_b32_e32 v25, v0
	v_mov_b32_e32 v26, v0
	v_mov_b32_e32 v27, v0
	v_mov_b32_e32 v28, v0
	v_mov_b32_e32 v29, v0
	v_mov_b32_e32 v30, v0
	v_mov_b32_e32 v31, v0
	v_mov_b32_e32 v32, v0
	v_mov_b32_e32 v33, v0
	v_mov_b32_e32 v34, v0
	v_mov_b32_e32 v35, v0
	v_mov_b32_e32 v36, v0
	v_mov_b32_e32 v37, v0
	v_mov_b32_e32 v38, v0
	v_mov_b32_e32 v39, v0
	v_mov_b32_e32 v40, v0
	v_mov_b32_e32 v41, v0
	v_mov_b32_e32 v42, v0
	v_mov_b32_e32 v43, v0
	v_mov_b32_e32 v44, v0
	v_mov_b32_e32 v45, v0
	v_mov_b32_e32 v46, v0
	v_mov_b32_e32 v47, v0
	v_mov_b32_e32 v48, v0
	v_mov_b32_e32 v49, v0
	v_mov_b32_e32 v50, v0
	v_mov_b32_e32 v51, v0
	v_mov_b32_e32 v52, v0
	v_mov_b32_e32 v53, v0
	v_mov_b32_e32 v54, v0
	v_mov_b32_e32 v55, v0
	v_mov_b32_e32 v56, v0
	v_mov_b32_e32 v57, v0
	v_mov_b32_e32 v58, v0
	v_mov_b32_e32 v59, v0
	v_mov_b32_e32 v60, v0
	v_mov_b32_e32 v61, v0
	v_mov_b32_e32 v62, v0
	v_mov_b32_e32 v63, v0
	s_waitcnt vmcnt(29)
	ds_write_b128 v156, v[68:71]
	ds_write_b128 v156, v[64:67] offset:4096
	ds_write_b128 v156, v[72:75] offset:8192
	s_waitcnt vmcnt(27)
	ds_write_b128 v156, v[80:83] offset:12288
	ds_write_b128 v156, v[76:79] offset:16384
	s_waitcnt vmcnt(26)
	ds_write_b128 v156, v[84:87] offset:20480
	s_waitcnt vmcnt(25)
	ds_write_b128 v156, v[88:91] offset:24576
	s_waitcnt vmcnt(24)
	ds_write_b128 v156, v[92:95] offset:28672
	s_waitcnt lgkmcnt(0)
	s_barrier

.LBB0_89:
	s_and_b64 vcc, exec, s[0:1]
	s_cbranch_vccz .LBB0_125
	v_readlane_b32 s0, v250, 13
	v_readlane_b32 s1, v250, 14
	s_and_b64 vcc, exec, s[0:1]
	s_cbranch_vccz .LBB0_125
	v_readlane_b32 s0, v254, 54
	v_readlane_b32 s1, v254, 55
	s_lshl_b32 s0, s69, 21
	v_readlane_b32 s1, v250, 63
	s_add_u32 s2, s1, s0
	v_readlane_b32 s0, v251, 0
	s_waitcnt vmcnt(21)
	v_mov_b32_e32 v44, v166
	s_addc_u32 s3, s0, 0
	v_readlane_b32 s0, v251, 5
	v_ashrrev_i32_e32 v106, 3, v44
	v_lshlrev_b32_e32 v2, 3, v44
	v_add_u32_e32 v0, s0, v106
	s_waitcnt lgkmcnt(0)
	v_ashrrev_i32_e32 v1, 31, v0
	v_readlane_b32 s0, v251, 20
	v_lshlrev_b64 v[0:1], 11, v[0:1]
	v_readlane_b32 s1, v251, 21
	v_and_b32_e32 v96, 56, v2
	v_lshlrev_b32_e32 v128, 1, v96
	v_lshl_add_u64 v[0:1], s[0:1], 0, v[0:1]
	v_lshl_add_u64 v[98:99], v[0:1], 0, v[128:129]
	v_readlane_b32 s0, v251, 6
	s_waitcnt vmcnt(11)
	v_add_co_u32_e32 v32, vcc, s11, v98
	v_add_u32_e32 v0, s0, v106
	s_nop 0
	v_addc_co_u32_e32 v33, vcc, 0, v99, vcc
	v_ashrrev_i32_e32 v1, 31, v0
	v_add_co_u32_e32 v34, vcc, s33, v98
	v_lshlrev_b64 v[0:1], 11, v[0:1]
	s_nop 0
	v_addc_co_u32_e32 v35, vcc, 0, v99, vcc
	v_lshl_add_u64 v[0:1], s[2:3], 0, v[0:1]
	v_add_co_u32_e32 v36, vcc, s59, v98
	v_lshl_add_u64 v[100:101], v[0:1], 0, v[128:129]
	s_nop 0
	v_addc_co_u32_e32 v37, vcc, 0, v99, vcc
	v_add_co_u32_e32 v38, vcc, s11, v100
	global_load_dwordx4 v[0:3], v[32:33], off
	global_load_dwordx4 v[4:7], v[34:35], off
	v_addc_co_u32_e32 v39, vcc, 0, v101, vcc
	v_add_co_u32_e32 v40, vcc, s33, v100
	s_waitcnt lgkmcnt(0)
	global_load_dwordx4 v[8:11], v[98:99], off
	global_load_dwordx4 v[12:15], v[100:101], off
	v_addc_co_u32_e32 v41, vcc, 0, v101, vcc
	v_add_co_u32_e32 v42, vcc, s59, v100
	global_load_dwordx4 v[16:19], v[36:37], off
	global_load_dwordx4 v[20:23], v[38:39], off
	v_addc_co_u32_e32 v43, vcc, 0, v101, vcc
	global_load_dwordx4 v[24:27], v[40:41], off
	global_load_dwordx4 v[28:31], v[42:43], off
	global_load_dwordx4 v[60:63], v[32:33], off offset:128
	global_load_dwordx4 v[64:67], v[34:35], off offset:128
	global_load_dwordx4 v[56:59], v[98:99], off offset:128
	global_load_dwordx4 v[68:71], v[100:101], off offset:128
	global_load_dwordx4 v[72:75], v[36:37], off offset:128
	global_load_dwordx4 v[76:79], v[38:39], off offset:128
	global_load_dwordx4 v[80:83], v[40:41], off offset:128
	global_load_dwordx4 v[84:87], v[42:43], off offset:128
	v_ashrrev_i32_e32 v46, 1, v44
	v_lshlrev_b32_e32 v47, 4, v44
	v_and_b32_e32 v107, 15, v44
	v_lshrrev_b32_e32 v45, 4, v44
	v_bfe_u32 v97, v44, 4, 2
	v_bfe_u32 v102, v44, 6, 1
	s_waitcnt vmcnt(25)
	v_bfe_u32 v48, v44, 1, 3
	v_and_b32_e32 v108, 0xffffffc0, v46
	v_lshlrev_b32_e32 v46, 7, v106
	v_xor_b32_e32 v44, v47, v44
	s_movk_i32 s0, 0x70
	v_and_or_b32 v44, v44, s0, v46
	v_add_u32_e32 v109, 0, v44
	v_lshlrev_b32_e32 v47, 7, v107
	v_or_b32_e32 v46, v108, v107
	v_lshl_or_b32 v47, v102, 13, v47
	s_mov_b64 s[50:51], s[78:79]
	v_lshl_add_u32 v103, v46, 7, 0
	v_add_u32_e32 v104, 0, v47
	s_mov_b32 s1, -2
	s_waitcnt vmcnt(13)
	ds_write_b128 v109, v[8:11]
	s_waitcnt vmcnt(12)
	ds_write_b128 v109, v[12:15] offset:16384
	ds_write_b128 v109, v[0:3] offset:4096
	ds_write_b128 v109, v[4:7] offset:8192
	s_waitcnt vmcnt(11)
	ds_write_b128 v109, v[16:19] offset:12288
	s_waitcnt vmcnt(10)
	ds_write_b128 v109, v[20:23] offset:20480
	s_waitcnt vmcnt(9)
	ds_write_b128 v109, v[24:27] offset:24576
	s_waitcnt vmcnt(8)
	ds_write_b128 v109, v[28:31] offset:28672
	v_bitop3_b32 v0, v48, v45, 3 bitop3:0x78
	v_lshlrev_b32_e32 v105, 4, v0
	v_bitop3_b32 v0, v97, v48, 4 bitop3:0x36
	v_lshlrev_b32_e32 v114, 4, v0
	v_mov_b32_e32 v0, 0
	v_mov_b32_e32 v1, v0
	v_mov_b32_e32 v2, v0
	v_mov_b32_e32 v3, v0
	v_mov_b32_e32 v4, v0
	v_mov_b32_e32 v5, v0
	v_mov_b32_e32 v6, v0
	v_mov_b32_e32 v7, v0
	v_mov_b32_e32 v8, v0
	v_mov_b32_e32 v9, v0
	v_mov_b32_e32 v10, v0
	v_mov_b32_e32 v11, v0
	v_mov_b32_e32 v12, v0
	v_mov_b32_e32 v13, v0
	v_mov_b32_e32 v14, v0
	v_mov_b32_e32 v15, v0
	v_mov_b32_e32 v16, v0
	v_mov_b32_e32 v17, v0
	v_mov_b32_e32 v18, v0
	v_mov_b32_e32 v19, v0
	v_mov_b32_e32 v20, v0
	v_mov_b32_e32 v21, v0
	v_mov_b32_e32 v22, v0
	v_mov_b32_e32 v23, v0
	v_mov_b32_e32 v24, v0
	v_mov_b32_e32 v25, v0
	v_mov_b32_e32 v26, v0
	v_mov_b32_e32 v27, v0
	v_mov_b32_e32 v28, v0
	v_mov_b32_e32 v29, v0
	v_mov_b32_e32 v30, v0
	v_mov_b32_e32 v31, v0
	v_mov_b32_e32 v32, v0
	v_mov_b32_e32 v33, v0
	v_mov_b32_e32 v34, v0
	v_mov_b32_e32 v35, v0
	v_mov_b32_e32 v36, v0
	v_mov_b32_e32 v37, v0
	v_mov_b32_e32 v38, v0
	v_mov_b32_e32 v39, v0
	v_mov_b32_e32 v40, v0
	v_mov_b32_e32 v41, v0
	v_mov_b32_e32 v42, v0
	v_mov_b32_e32 v43, v0
	v_mov_b32_e32 v44, v0
	v_mov_b32_e32 v45, v0
	v_mov_b32_e32 v46, v0
	v_mov_b32_e32 v47, v0
	v_mov_b32_e32 v48, v0
	v_mov_b32_e32 v49, v0
	v_mov_b32_e32 v50, v0
	v_mov_b32_e32 v51, v0
	v_mov_b32_e32 v52, v0
	v_mov_b32_e32 v53, v0
	v_mov_b32_e32 v54, v0
	v_mov_b32_e32 v55, v0
	v_mov_b32_e32 v88, v0
	v_mov_b32_e32 v89, v0
	v_mov_b32_e32 v90, v0
	v_mov_b32_e32 v91, v0
	v_mov_b32_e32 v92, v0
	v_mov_b32_e32 v93, v0
	v_mov_b32_e32 v94, v0
	v_mov_b32_e32 v95, v0
	s_waitcnt lgkmcnt(0)
	s_barrier

.LBB0_105:
	s_ashr_i32 s24, s28, 31
	s_lshr_b32 s24, s24, 27
	s_add_i32 s24, s28, s24
	s_and_b32 s25, s24, 0xffffffe0
	s_sub_i32 s25, s28, s25
	s_lshl_b32 s24, s24, 4
	s_lshl_b32 s29, s25, 7
	s_and_b32 s24, s24, 0xfffffe00
	s_and_b32 s29, s29, 0x180
	s_or_b32 s24, s29, s24
	v_add_u32_e32 v0, s24, v106
	s_lshl_b32 s25, s25, 5
	s_waitcnt lgkmcnt(0)
	v_ashrrev_i32_e32 v1, 31, v0
	s_and_b32 s25, s25, 0xffffff80
	v_lshlrev_b64 v[0:1], 11, v[0:1]
	v_lshl_add_u64 v[100:101], v[96:97], 0, v[0:1]
	v_add_u32_e32 v0, s25, v106
	v_ashrrev_i32_e32 v1, 31, v0
	v_lshlrev_b64 v[0:1], 11, v[0:1]
	v_lshl_add_u64 v[102:103], v[98:99], 0, v[0:1]
	v_add_co_u32_e32 v0, vcc, s11, v100
	s_mov_b32 s44, -2
	s_nop 0
	v_addc_co_u32_e32 v1, vcc, 0, v101, vcc
	v_add_co_u32_e32 v2, vcc, s33, v100
	s_nop 1
	v_addc_co_u32_e32 v3, vcc, 0, v101, vcc
	v_add_co_u32_e32 v4, vcc, s59, v100
	global_load_dwordx4 v[20:23], v[0:1], off
	global_load_dwordx4 v[24:27], v[2:3], off
	v_addc_co_u32_e32 v5, vcc, 0, v101, vcc
	v_add_co_u32_e32 v6, vcc, s33, v102
	global_load_dwordx4 v[28:31], v[100:101], off
	global_load_dwordx4 v[32:35], v[102:103], off
	v_addc_co_u32_e32 v7, vcc, 0, v103, vcc
	v_add_co_u32_e32 v8, vcc, s59, v102
	s_nop 1
	v_addc_co_u32_e32 v9, vcc, 0, v103, vcc
	v_add_co_u32_e32 v10, vcc, s11, v102
	global_load_dwordx4 v[36:39], v[6:7], off
	global_load_dwordx4 v[40:43], v[8:9], off
	v_addc_co_u32_e32 v11, vcc, 0, v103, vcc
	global_load_dwordx4 v[44:47], v[4:5], off
	global_load_dwordx4 v[48:51], v[10:11], off
	global_load_dwordx4 v[60:63], v[0:1], off offset:128
	global_load_dwordx4 v[64:67], v[2:3], off offset:128
	global_load_dwordx4 v[52:55], v[100:101], off offset:128
	global_load_dwordx4 v[68:71], v[102:103], off offset:128
	global_load_dwordx4 v[72:75], v[4:5], off offset:128
	global_load_dwordx4 v[76:79], v[10:11], off offset:128
	global_load_dwordx4 v[80:83], v[6:7], off offset:128
	global_load_dwordx4 v[84:87], v[8:9], off offset:128
	v_mov_b32_e32 v0, 0
	v_mov_b32_e32 v1, v0
	v_mov_b32_e32 v2, v0
	v_mov_b32_e32 v3, v0
	v_mov_b32_e32 v4, v0
	v_mov_b32_e32 v5, v0
	v_mov_b32_e32 v6, v0
	v_mov_b32_e32 v7, v0
	v_mov_b32_e32 v8, v0
	v_mov_b32_e32 v9, v0
	v_mov_b32_e32 v10, v0
	v_mov_b32_e32 v11, v0
	v_mov_b32_e32 v12, v0
	v_mov_b32_e32 v13, v0
	v_mov_b32_e32 v14, v0
	v_mov_b32_e32 v15, v0
	v_mov_b32_e32 v16, v0
	v_mov_b32_e32 v17, v0
	v_mov_b32_e32 v18, v0
	v_mov_b32_e32 v19, v0
	v_mov_b32_e32 v56, v0
	v_mov_b32_e32 v57, v0
	v_mov_b32_e32 v58, v0
	v_mov_b32_e32 v59, v0
	v_mov_b32_e32 v88, v0
	v_mov_b32_e32 v89, v0
	v_mov_b32_e32 v90, v0
	v_mov_b32_e32 v91, v0
	v_mov_b32_e32 v92, v0
	v_mov_b32_e32 v93, v0
	v_mov_b32_e32 v94, v0
	v_mov_b32_e32 v95, v0
	s_waitcnt vmcnt(13)
	ds_write_b128 v109, v[28:31]
	s_waitcnt vmcnt(12)
	ds_write_b128 v109, v[32:35] offset:16384
	s_waitcnt vmcnt(11)
	ds_write_b128 v109, v[36:39] offset:24576
	s_waitcnt vmcnt(10)
	ds_write_b128 v109, v[40:43] offset:28672
	ds_write_b128 v109, v[20:23] offset:4096
	ds_write_b128 v109, v[24:27] offset:8192
	s_waitcnt vmcnt(9)
	ds_write_b128 v109, v[44:47] offset:12288
	s_waitcnt vmcnt(8)
	ds_write_b128 v109, v[48:51] offset:20480
	v_mov_b32_e32 v20, v0
	v_mov_b32_e32 v21, v0
	v_mov_b32_e32 v22, v0
	v_mov_b32_e32 v23, v0
	v_mov_b32_e32 v24, v0
	v_mov_b32_e32 v25, v0
	v_mov_b32_e32 v26, v0
	v_mov_b32_e32 v27, v0
	v_mov_b32_e32 v28, v0
	v_mov_b32_e32 v29, v0
	v_mov_b32_e32 v30, v0
	v_mov_b32_e32 v31, v0
	v_mov_b32_e32 v32, v0
	v_mov_b32_e32 v33, v0
	v_mov_b32_e32 v34, v0
	v_mov_b32_e32 v35, v0
	v_mov_b32_e32 v36, v0
	v_mov_b32_e32 v37, v0
	v_mov_b32_e32 v38, v0
	v_mov_b32_e32 v39, v0
	v_mov_b32_e32 v40, v0
	v_mov_b32_e32 v41, v0
	v_mov_b32_e32 v42, v0
	v_mov_b32_e32 v43, v0
	v_mov_b32_e32 v44, v0
	v_mov_b32_e32 v45, v0
	v_mov_b32_e32 v46, v0
	v_mov_b32_e32 v47, v0
	v_mov_b32_e32 v48, v0
	v_mov_b32_e32 v49, v0
	v_mov_b32_e32 v50, v0
	v_mov_b32_e32 v51, v0
	s_waitcnt lgkmcnt(0)
	s_barrier

.LBB0_116:
	s_andn2_b64 vcc, exec, s[24:25]
	s_cbranch_vccnz .LBB0_125
	v_readlane_b32 s16, v251, 16
	v_readlane_b32 s17, v251, 17
	s_andn2_b64 vcc, exec, s[16:17]
	s_cbranch_vccnz .LBB0_125
	v_mov_b32_e32 v0, v166
	s_movk_i32 s16, 0x70
	s_waitcnt lgkmcnt(0)
	v_ashrrev_i32_e32 v1, 1, v0
	v_ashrrev_i32_e32 v2, 3, v0
	v_lshlrev_b32_e32 v3, 4, v0
	v_and_b32_e32 v86, 0xffffffe0, v1
	v_lshlrev_b32_e32 v1, 7, v2
	v_xor_b32_e32 v4, v3, v0
	v_and_or_b32 v28, v4, s16, v1
	v_readlane_b32 s16, v251, 18
	v_and_b32_e32 v85, 15, v0
	v_lshrrev_b32_e32 v40, 4, v0
	v_bfe_u32 v84, v0, 4, 2
	v_bfe_u32 v41, v0, 1, 3
	v_add_u32_e32 v0, s16, v2
	v_ashrrev_i32_e32 v1, 31, v0
	v_readlane_b32 s16, v251, 20
	v_lshlrev_b64 v[0:1], 11, v[0:1]
	v_readlane_b32 s17, v251, 21
	v_and_b32_e32 v128, 0x70, v3
	v_add_u32_e32 v87, 0, v28
	v_lshl_add_u64 v[0:1], s[16:17], 0, v[0:1]
	v_lshl_add_u64 v[80:81], v[0:1], 0, v[128:129]
	v_add_co_u32_e32 v24, vcc, s11, v80
	v_readlane_b32 s16, v251, 19
	s_nop 0
	v_addc_co_u32_e32 v25, vcc, 0, v81, vcc
	v_add_u32_e32 v0, s16, v2
	v_add_co_u32_e32 v26, vcc, s33, v80
	v_ashrrev_i32_e32 v1, 31, v0
	s_nop 0
	v_addc_co_u32_e32 v27, vcc, 0, v81, vcc
	v_lshlrev_b64 v[0:1], 11, v[0:1]
	v_add_co_u32_e32 v36, vcc, s59, v80
	v_lshl_add_u64 v[0:1], s[2:3], 0, v[0:1]
	s_nop 0
	v_addc_co_u32_e32 v37, vcc, 0, v81, vcc
	v_lshl_add_u64 v[82:83], v[0:1], 0, v[128:129]
	global_load_dwordx4 v[0:3], v[80:81], off
	global_load_dwordx4 v[4:7], v[24:25], off
	global_load_dwordx4 v[8:11], v[26:27], off
	global_load_dwordx4 v[12:15], v[36:37], off
	global_load_dwordx4 v[16:19], v[82:83], off
	v_add_co_u32_e32 v38, vcc, s11, v82
	v_or_b32_e32 v42, v86, v85
	s_nop 0
	v_addc_co_u32_e32 v39, vcc, 0, v83, vcc
	global_load_dwordx4 v[20:23], v[38:39], off
	v_lshl_add_u32 v88, v42, 7, 0
	v_lshl_add_u32 v89, v85, 7, 0
	s_mov_b32 s3, -2
	s_waitcnt vmcnt(5)
	ds_write_b128 v87, v[0:3]
	s_waitcnt vmcnt(4)
	ds_write_b128 v87, v[4:7] offset:4096
	s_waitcnt vmcnt(3)
	ds_write_b128 v87, v[8:11] offset:8192
	s_waitcnt vmcnt(2)
	ds_write_b128 v87, v[12:15] offset:12288
	s_waitcnt vmcnt(1)
	ds_write_b128 v87, v[16:19] offset:16384
	s_waitcnt vmcnt(0)
	ds_write_b128 v87, v[20:23] offset:20480
	global_load_dwordx4 v[28:31], v[80:81], off offset:128
	global_load_dwordx4 v[32:35], v[24:25], off offset:128
	s_nop 0
	global_load_dwordx4 v[24:27], v[26:27], off offset:128
	s_nop 0
	global_load_dwordx4 v[20:23], v[36:37], off offset:128
	global_load_dwordx4 v[16:19], v[82:83], off offset:128
	global_load_dwordx4 v[12:15], v[38:39], off offset:128
	v_bitop3_b32 v0, v41, v40, 3 bitop3:0x78
	v_lshlrev_b32_e32 v90, 4, v0
	v_bitop3_b32 v0, v84, v41, 4 bitop3:0x36
	v_lshlrev_b32_e32 v91, 4, v0
	v_mov_b32_e32 v0, 0
	v_mov_b32_e32 v1, v0
	v_mov_b32_e32 v2, v0
	v_mov_b32_e32 v3, v0
	v_mov_b32_e32 v4, v0
	v_mov_b32_e32 v5, v0
	v_mov_b32_e32 v6, v0
	v_mov_b32_e32 v7, v0
	v_mov_b32_e32 v8, v0
	v_mov_b32_e32 v9, v0
	v_mov_b32_e32 v10, v0
	v_mov_b32_e32 v11, v0
	v_mov_b32_e32 v36, v0
	v_mov_b32_e32 v37, v0
	v_mov_b32_e32 v38, v0
	v_mov_b32_e32 v39, v0
	v_mov_b32_e32 v40, v0
	v_mov_b32_e32 v41, v0
	v_mov_b32_e32 v42, v0
	v_mov_b32_e32 v43, v0
	v_mov_b32_e32 v52, v0
	v_mov_b32_e32 v53, v0
	v_mov_b32_e32 v54, v0
	v_mov_b32_e32 v55, v0
	v_mov_b32_e32 v68, v0
	v_mov_b32_e32 v69, v0
	v_mov_b32_e32 v70, v0
	v_mov_b32_e32 v71, v0
	v_mov_b32_e32 v76, v0
	v_mov_b32_e32 v77, v0
	v_mov_b32_e32 v78, v0
	v_mov_b32_e32 v79, v0
	s_waitcnt lgkmcnt(0)
	s_barrier

.LBB0_233:
	s_and_b64 vcc, exec, s[78:79]
	s_cbranch_vccz .LBB0_350
	v_readlane_b32 s0, v250, 13
	v_readlane_b32 s1, v250, 14
	s_and_b64 vcc, exec, s[0:1]
	s_cbranch_vccz .LBB0_349
	s_waitcnt vmcnt(21)
	v_mov_b32_e32 v44, v166
	v_readlane_b32 s16, v251, 5
	v_ashrrev_i32_e32 v106, 3, v44
	v_lshlrev_b32_e32 v2, 3, v44
	v_add_u32_e32 v0, s16, v106
	s_waitcnt lgkmcnt(0)
	v_ashrrev_i32_e32 v1, 31, v0
	v_lshlrev_b64 v[0:1], 13, v[0:1]
	v_and_b32_e32 v96, 56, v2
	v_lshl_add_u64 v[0:1], s[30:31], 0, v[0:1]
	v_lshlrev_b32_e32 v128, 1, v96
	v_readlane_b32 s8, v254, 54
	v_lshl_add_u64 v[98:99], v[0:1], 0, v[128:129]
	v_readlane_b32 s9, v254, 55
	v_readlane_b32 s16, v251, 6
	s_waitcnt vmcnt(11)
	v_add_co_u32_e32 v32, vcc, s7, v98
	s_xor_b64 s[2:3], s[8:9], -1
	s_lshl_b32 s0, s69, 23
	v_readlane_b32 s1, v250, 59
	v_add_u32_e32 v0, s16, v106
	v_addc_co_u32_e32 v33, vcc, 0, v99, vcc
	s_add_u32 s0, s1, s0
	v_readlane_b32 s1, v250, 60
	v_ashrrev_i32_e32 v1, 31, v0
	v_add_co_u32_e32 v34, vcc, s52, v98
	s_addc_u32 s1, s1, 0
	v_lshlrev_b64 v[0:1], 13, v[0:1]
	v_addc_co_u32_e32 v35, vcc, 0, v99, vcc
	v_lshl_add_u64 v[0:1], s[0:1], 0, v[0:1]
	v_add_co_u32_e32 v36, vcc, s34, v98
	v_lshl_add_u64 v[100:101], v[0:1], 0, v[128:129]
	s_nop 0
	v_addc_co_u32_e32 v37, vcc, 0, v99, vcc
	v_add_co_u32_e32 v38, vcc, s7, v100
	global_load_dwordx4 v[0:3], v[32:33], off
	global_load_dwordx4 v[4:7], v[34:35], off
	v_addc_co_u32_e32 v39, vcc, 0, v101, vcc
	v_add_co_u32_e32 v40, vcc, s52, v100
	global_load_dwordx4 v[8:11], v[98:99], off
	global_load_dwordx4 v[12:15], v[100:101], off
	v_addc_co_u32_e32 v41, vcc, 0, v101, vcc
	v_add_co_u32_e32 v42, vcc, s34, v100
	global_load_dwordx4 v[16:19], v[36:37], off
	global_load_dwordx4 v[20:23], v[38:39], off
	v_addc_co_u32_e32 v43, vcc, 0, v101, vcc
	global_load_dwordx4 v[24:27], v[40:41], off
	global_load_dwordx4 v[28:31], v[42:43], off
	global_load_dwordx4 v[64:67], v[32:33], off offset:128
	global_load_dwordx4 v[68:71], v[34:35], off offset:128
	global_load_dwordx4 v[60:63], v[98:99], off offset:128
	global_load_dwordx4 v[72:75], v[100:101], off offset:128
	global_load_dwordx4 v[76:79], v[36:37], off offset:128
	global_load_dwordx4 v[80:83], v[38:39], off offset:128
	global_load_dwordx4 v[84:87], v[40:41], off offset:128
	global_load_dwordx4 v[88:91], v[42:43], off offset:128
	v_ashrrev_i32_e32 v46, 1, v44
	v_lshlrev_b32_e32 v47, 4, v44
	v_and_b32_e32 v107, 15, v44
	v_lshrrev_b32_e32 v45, 4, v44
	v_bfe_u32 v97, v44, 4, 2
	v_bfe_u32 v102, v44, 6, 1
	s_waitcnt vmcnt(25)
	v_bfe_u32 v48, v44, 1, 3
	v_and_b32_e32 v108, 0xffffffc0, v46
	v_lshlrev_b32_e32 v46, 7, v106
	v_xor_b32_e32 v44, v47, v44
	s_movk_i32 s16, 0x70
	v_and_or_b32 v44, v44, s16, v46
	v_add_u32_e32 v109, 0, v44
	v_lshlrev_b32_e32 v47, 7, v107
	v_or_b32_e32 v46, v108, v107
	v_lshl_or_b32 v47, v102, 13, v47
	v_lshl_add_u32 v103, v46, 7, 0
	v_add_u32_e32 v104, 0, v47
	s_mov_b32 s25, -2
	s_waitcnt vmcnt(13)
	ds_write_b128 v109, v[8:11]
	s_waitcnt vmcnt(12)
	ds_write_b128 v109, v[12:15] offset:16384
	ds_write_b128 v109, v[0:3] offset:4096
	ds_write_b128 v109, v[4:7] offset:8192
	s_waitcnt vmcnt(11)
	ds_write_b128 v109, v[16:19] offset:12288
	s_waitcnt vmcnt(10)
	ds_write_b128 v109, v[20:23] offset:20480
	s_waitcnt vmcnt(9)
	ds_write_b128 v109, v[24:27] offset:24576
	s_waitcnt vmcnt(8)
	ds_write_b128 v109, v[28:31] offset:28672
	v_bitop3_b32 v0, v48, v45, 3 bitop3:0x78
	v_lshlrev_b32_e32 v105, 4, v0
	v_bitop3_b32 v0, v97, v48, 4 bitop3:0x36
	v_lshlrev_b32_e32 v114, 4, v0
	v_mov_b32_e32 v0, 0
	v_mov_b32_e32 v1, v0
	v_mov_b32_e32 v2, v0
	v_mov_b32_e32 v3, v0
	v_mov_b32_e32 v4, v0
	v_mov_b32_e32 v5, v0
	v_mov_b32_e32 v6, v0
	v_mov_b32_e32 v7, v0
	v_mov_b32_e32 v8, v0
	v_mov_b32_e32 v9, v0
	v_mov_b32_e32 v10, v0
	v_mov_b32_e32 v11, v0
	v_mov_b32_e32 v12, v0
	v_mov_b32_e32 v13, v0
	v_mov_b32_e32 v14, v0
	v_mov_b32_e32 v15, v0
	v_mov_b32_e32 v16, v0
	v_mov_b32_e32 v17, v0
	v_mov_b32_e32 v18, v0
	v_mov_b32_e32 v19, v0
	v_mov_b32_e32 v20, v0
	v_mov_b32_e32 v21, v0
	v_mov_b32_e32 v22, v0
	v_mov_b32_e32 v23, v0
	v_mov_b32_e32 v24, v0
	v_mov_b32_e32 v25, v0
	v_mov_b32_e32 v26, v0
	v_mov_b32_e32 v27, v0
	v_mov_b32_e32 v28, v0
	v_mov_b32_e32 v29, v0
	v_mov_b32_e32 v30, v0
	v_mov_b32_e32 v31, v0
	v_mov_b32_e32 v32, v0
	v_mov_b32_e32 v33, v0
	v_mov_b32_e32 v34, v0
	v_mov_b32_e32 v35, v0
	v_mov_b32_e32 v36, v0
	v_mov_b32_e32 v37, v0
	v_mov_b32_e32 v38, v0
	v_mov_b32_e32 v39, v0
	v_mov_b32_e32 v40, v0
	v_mov_b32_e32 v41, v0
	v_mov_b32_e32 v42, v0
	v_mov_b32_e32 v43, v0
	v_mov_b32_e32 v44, v0
	v_mov_b32_e32 v45, v0
	v_mov_b32_e32 v46, v0
	v_mov_b32_e32 v47, v0
	v_mov_b32_e32 v48, v0
	v_mov_b32_e32 v49, v0
	v_mov_b32_e32 v50, v0
	v_mov_b32_e32 v51, v0
	v_mov_b32_e32 v52, v0
	v_mov_b32_e32 v53, v0
	v_mov_b32_e32 v54, v0
	v_mov_b32_e32 v55, v0
	v_mov_b32_e32 v56, v0
	v_mov_b32_e32 v57, v0
	v_mov_b32_e32 v58, v0
	v_mov_b32_e32 v59, v0
	v_mov_b32_e32 v92, v0
	v_mov_b32_e32 v93, v0
	v_mov_b32_e32 v94, v0
	v_mov_b32_e32 v95, v0
	s_waitcnt lgkmcnt(0)
	s_barrier

.LBB0_281:
	s_ashr_i32 s2, s24, 31
	s_lshr_b32 s2, s2, 27
	s_add_i32 s2, s24, s2
	s_and_b32 s3, s2, 0xffffffe0
	s_sub_i32 s3, s24, s3
	s_lshl_b32 s2, s2, 4
	s_lshl_b32 s25, s3, 7
	s_and_b32 s2, s2, 0xfffffe00
	s_and_b32 s25, s25, 0x180
	s_or_b32 s2, s25, s2
	v_add_u32_e32 v0, s2, v106
	s_lshl_b32 s3, s3, 5
	s_waitcnt lgkmcnt(0)
	v_ashrrev_i32_e32 v1, 31, v0
	s_and_b32 s3, s3, 0xffffff80
	v_lshlrev_b64 v[0:1], 13, v[0:1]
	v_lshl_add_u64 v[100:101], v[96:97], 0, v[0:1]
	v_add_u32_e32 v0, s3, v106
	v_ashrrev_i32_e32 v1, 31, v0
	v_lshlrev_b64 v[0:1], 13, v[0:1]
	v_lshl_add_u64 v[102:103], v[98:99], 0, v[0:1]
	v_add_co_u32_e32 v0, vcc, s7, v100
	s_mov_b32 s28, -2
	s_nop 0
	v_addc_co_u32_e32 v1, vcc, 0, v101, vcc
	v_add_co_u32_e32 v2, vcc, s52, v100
	s_nop 1
	v_addc_co_u32_e32 v3, vcc, 0, v101, vcc
	v_add_co_u32_e32 v4, vcc, s34, v100
	global_load_dwordx4 v[20:23], v[0:1], off
	global_load_dwordx4 v[24:27], v[2:3], off
	v_addc_co_u32_e32 v5, vcc, 0, v101, vcc
	v_add_co_u32_e32 v6, vcc, s52, v102
	global_load_dwordx4 v[28:31], v[100:101], off
	global_load_dwordx4 v[32:35], v[102:103], off
	v_addc_co_u32_e32 v7, vcc, 0, v103, vcc
	v_add_co_u32_e32 v8, vcc, s34, v102
	s_nop 1
	v_addc_co_u32_e32 v9, vcc, 0, v103, vcc
	v_add_co_u32_e32 v10, vcc, s7, v102
	global_load_dwordx4 v[36:39], v[6:7], off
	global_load_dwordx4 v[40:43], v[8:9], off
	v_addc_co_u32_e32 v11, vcc, 0, v103, vcc
	global_load_dwordx4 v[44:47], v[4:5], off
	global_load_dwordx4 v[48:51], v[10:11], off
	global_load_dwordx4 v[64:67], v[0:1], off offset:128
	global_load_dwordx4 v[68:71], v[2:3], off offset:128
	global_load_dwordx4 v[60:63], v[100:101], off offset:128
	global_load_dwordx4 v[72:75], v[102:103], off offset:128
	global_load_dwordx4 v[76:79], v[4:5], off offset:128
	global_load_dwordx4 v[80:83], v[10:11], off offset:128
	global_load_dwordx4 v[84:87], v[6:7], off offset:128
	global_load_dwordx4 v[88:91], v[8:9], off offset:128
	v_mov_b32_e32 v0, 0
	v_mov_b32_e32 v1, v0
	v_mov_b32_e32 v2, v0
	v_mov_b32_e32 v3, v0
	v_mov_b32_e32 v4, v0
	v_mov_b32_e32 v5, v0
	v_mov_b32_e32 v6, v0
	v_mov_b32_e32 v7, v0
	v_mov_b32_e32 v8, v0
	v_mov_b32_e32 v9, v0
	v_mov_b32_e32 v10, v0
	v_mov_b32_e32 v11, v0
	v_mov_b32_e32 v12, v0
	v_mov_b32_e32 v13, v0
	v_mov_b32_e32 v14, v0
	v_mov_b32_e32 v15, v0
	v_mov_b32_e32 v16, v0
	v_mov_b32_e32 v17, v0
	v_mov_b32_e32 v18, v0
	v_mov_b32_e32 v19, v0
	v_mov_b32_e32 v52, v0
	v_mov_b32_e32 v53, v0
	v_mov_b32_e32 v54, v0
	v_mov_b32_e32 v55, v0
	v_mov_b32_e32 v56, v0
	v_mov_b32_e32 v57, v0
	v_mov_b32_e32 v58, v0
	v_mov_b32_e32 v59, v0
	v_mov_b32_e32 v92, v0
	v_mov_b32_e32 v93, v0
	v_mov_b32_e32 v94, v0
	v_mov_b32_e32 v95, v0
	s_waitcnt vmcnt(13)
	ds_write_b128 v109, v[28:31]
	s_waitcnt vmcnt(12)
	ds_write_b128 v109, v[32:35] offset:16384
	s_waitcnt vmcnt(11)
	ds_write_b128 v109, v[36:39] offset:24576
	s_waitcnt vmcnt(10)
	ds_write_b128 v109, v[40:43] offset:28672
	ds_write_b128 v109, v[20:23] offset:4096
	ds_write_b128 v109, v[24:27] offset:8192
	s_waitcnt vmcnt(9)
	ds_write_b128 v109, v[44:47] offset:12288
	s_waitcnt vmcnt(8)
	ds_write_b128 v109, v[48:51] offset:20480
	v_mov_b32_e32 v20, v0
	v_mov_b32_e32 v21, v0
	v_mov_b32_e32 v22, v0
	v_mov_b32_e32 v23, v0
	v_mov_b32_e32 v24, v0
	v_mov_b32_e32 v25, v0
	v_mov_b32_e32 v26, v0
	v_mov_b32_e32 v27, v0
	v_mov_b32_e32 v28, v0
	v_mov_b32_e32 v29, v0
	v_mov_b32_e32 v30, v0
	v_mov_b32_e32 v31, v0
	v_mov_b32_e32 v32, v0
	v_mov_b32_e32 v33, v0
	v_mov_b32_e32 v34, v0
	v_mov_b32_e32 v35, v0
	v_mov_b32_e32 v36, v0
	v_mov_b32_e32 v37, v0
	v_mov_b32_e32 v38, v0
	v_mov_b32_e32 v39, v0
	v_mov_b32_e32 v40, v0
	v_mov_b32_e32 v41, v0
	v_mov_b32_e32 v42, v0
	v_mov_b32_e32 v43, v0
	v_mov_b32_e32 v44, v0
	v_mov_b32_e32 v45, v0
	v_mov_b32_e32 v46, v0
	v_mov_b32_e32 v47, v0
	v_mov_b32_e32 v48, v0
	v_mov_b32_e32 v49, v0
	v_mov_b32_e32 v50, v0
	v_mov_b32_e32 v51, v0
	s_waitcnt lgkmcnt(0)
	s_barrier

.LBB0_324:
	s_andn2_b64 vcc, exec, s[2:3]
	s_cbranch_vccnz .LBB0_349
	v_readlane_b32 s2, v251, 16
	v_readlane_b32 s3, v251, 17
	s_andn2_b64 vcc, exec, s[2:3]
	s_cbranch_vccnz .LBB0_349
	v_mov_b32_e32 v0, v166
	s_movk_i32 s2, 0x70
	s_waitcnt lgkmcnt(0)
	v_ashrrev_i32_e32 v1, 1, v0
	v_ashrrev_i32_e32 v2, 3, v0
	v_lshlrev_b32_e32 v3, 4, v0
	v_and_b32_e32 v86, 0xffffffe0, v1
	v_lshlrev_b32_e32 v1, 7, v2
	v_xor_b32_e32 v4, v3, v0
	v_and_or_b32 v30, v4, s2, v1
	v_readlane_b32 s2, v251, 18
	v_and_b32_e32 v85, 15, v0
	v_lshrrev_b32_e32 v46, 4, v0
	v_bfe_u32 v84, v0, 4, 2
	v_bfe_u32 v47, v0, 1, 3
	v_add_u32_e32 v0, s2, v2
	v_ashrrev_i32_e32 v1, 31, v0
	v_lshlrev_b64 v[0:1], 13, v[0:1]
	v_lshl_add_u64 v[0:1], s[30:31], 0, v[0:1]
	v_and_b32_e32 v128, 0x70, v3
	v_lshl_add_u64 v[80:81], v[0:1], 0, v[128:129]
	v_add_co_u32_e32 v24, vcc, s7, v80
	v_readlane_b32 s2, v251, 19
	s_nop 0
	v_addc_co_u32_e32 v25, vcc, 0, v81, vcc
	v_add_u32_e32 v0, s2, v2
	v_add_co_u32_e32 v26, vcc, s52, v80
	v_ashrrev_i32_e32 v1, 31, v0
	s_nop 0
	v_addc_co_u32_e32 v27, vcc, 0, v81, vcc
	v_lshlrev_b64 v[0:1], 13, v[0:1]
	v_add_co_u32_e32 v28, vcc, s34, v80
	v_lshl_add_u64 v[0:1], s[0:1], 0, v[0:1]
	s_nop 0
	v_addc_co_u32_e32 v29, vcc, 0, v81, vcc
	v_lshl_add_u64 v[82:83], v[0:1], 0, v[128:129]
	global_load_dwordx4 v[0:3], v[80:81], off
	global_load_dwordx4 v[4:7], v[24:25], off
	global_load_dwordx4 v[8:11], v[26:27], off
	global_load_dwordx4 v[12:15], v[28:29], off
	global_load_dwordx4 v[16:19], v[82:83], off
	v_add_co_u32_e32 v44, vcc, s7, v82
	v_add_u32_e32 v87, 0, v30
	s_nop 0
	v_addc_co_u32_e32 v45, vcc, 0, v83, vcc
	global_load_dwordx4 v[20:23], v[44:45], off
	v_or_b32_e32 v48, v86, v85
	v_lshl_add_u32 v88, v48, 7, 0
	v_lshl_add_u32 v89, v85, 7, 0
	s_mov_b32 s1, -2
	s_waitcnt vmcnt(5)
	ds_write_b128 v87, v[0:3]
	s_waitcnt vmcnt(4)
	ds_write_b128 v87, v[4:7] offset:4096
	s_waitcnt vmcnt(3)
	ds_write_b128 v87, v[8:11] offset:8192
	s_waitcnt vmcnt(2)
	ds_write_b128 v87, v[12:15] offset:12288
	s_waitcnt vmcnt(1)
	ds_write_b128 v87, v[16:19] offset:16384
	s_waitcnt vmcnt(0)
	ds_write_b128 v87, v[20:23] offset:20480
	global_load_dwordx4 v[36:39], v[80:81], off offset:128
	global_load_dwordx4 v[40:43], v[24:25], off offset:128
	global_load_dwordx4 v[32:35], v[26:27], off offset:128
	s_nop 0
	global_load_dwordx4 v[28:31], v[28:29], off offset:128
	s_nop 0
	global_load_dwordx4 v[20:23], v[82:83], off offset:128
	global_load_dwordx4 v[16:19], v[44:45], off offset:128
	v_bitop3_b32 v0, v47, v46, 3 bitop3:0x78
	v_lshlrev_b32_e32 v90, 4, v0
	v_bitop3_b32 v0, v84, v47, 4 bitop3:0x36
	v_lshlrev_b32_e32 v91, 4, v0
	v_mov_b32_e32 v0, 0
	v_mov_b32_e32 v1, v0
	v_mov_b32_e32 v2, v0
	v_mov_b32_e32 v3, v0
	v_mov_b32_e32 v4, v0
	v_mov_b32_e32 v5, v0
	v_mov_b32_e32 v6, v0
	v_mov_b32_e32 v7, v0
	v_mov_b32_e32 v8, v0
	v_mov_b32_e32 v9, v0
	v_mov_b32_e32 v10, v0
	v_mov_b32_e32 v11, v0
	v_mov_b32_e32 v12, v0
	v_mov_b32_e32 v13, v0
	v_mov_b32_e32 v14, v0
	v_mov_b32_e32 v15, v0
	v_mov_b32_e32 v24, v0
	v_mov_b32_e32 v25, v0
	v_mov_b32_e32 v26, v0
	v_mov_b32_e32 v27, v0
	v_mov_b32_e32 v44, v0
	v_mov_b32_e32 v45, v0
	v_mov_b32_e32 v46, v0
	v_mov_b32_e32 v47, v0
	v_mov_b32_e32 v56, v0
	v_mov_b32_e32 v57, v0
	v_mov_b32_e32 v58, v0
	v_mov_b32_e32 v59, v0
	v_mov_b32_e32 v76, v0
	v_mov_b32_e32 v77, v0
	v_mov_b32_e32 v78, v0
	v_mov_b32_e32 v79, v0
	s_waitcnt lgkmcnt(0)
	s_barrier

.LBB0_358:
	s_lshl_b32 s26, s29, 7
	s_ashr_i32 s27, s26, 31
	v_lshl_add_u64 v[0:1], s[26:27], 2, v[136:137]
	s_mov_b32 s16, 0xa000
	v_add_co_u32_e32 v2, vcc, s16, v0
	s_mov_b32 s16, 0x14000
	s_nop 0
	v_addc_co_u32_e32 v3, vcc, 0, v1, vcc
	v_add_co_u32_e32 v4, vcc, s16, v0
	s_mov_b32 s16, 0x28000
	s_nop 0
	v_addc_co_u32_e32 v5, vcc, 0, v1, vcc
	v_add_co_u32_e32 v6, vcc, s12, v0
	s_nop 1
	v_addc_co_u32_e32 v7, vcc, 0, v1, vcc
	v_add_co_u32_e32 v8, vcc, s16, v0
	s_mov_b32 s16, 0x32000
	s_nop 0
	v_addc_co_u32_e32 v9, vcc, 0, v1, vcc
	v_add_co_u32_e32 v10, vcc, s16, v0
	s_mov_b32 s16, 0x46000
	s_nop 0
	v_addc_co_u32_e32 v11, vcc, 0, v1, vcc
	v_add_co_u32_e32 v12, vcc, s63, v0
	s_nop 0
	s_nop 0
	v_addc_co_u32_e32 v13, vcc, 0, v1, vcc
	v_add_co_u32_e32 v14, vcc, s16, v0
	s_mov_b32 s16, 0x50000
	s_nop 0
	v_addc_co_u32_e32 v15, vcc, 0, v1, vcc
	global_load_dword v128, v[0:1], off
	global_load_dword v157, v[2:3], off
	global_load_dword v158, v[4:5], off
	global_load_dword v159, v[6:7], off
	global_load_dword v160, v[8:9], off
	global_load_dword v161, v[10:11], off
	global_load_dword v162, v[12:13], off
	global_load_dword v163, v[14:15], off
	v_add_co_u32_e32 v2, vcc, s16, v0
	s_mov_b32 s16, 0x64000
	s_nop 0
	v_addc_co_u32_e32 v3, vcc, 0, v1, vcc
	v_add_co_u32_e32 v4, vcc, s57, v0
	s_lshl_b32 s40, s28, 7
	s_nop 0
	v_addc_co_u32_e32 v5, vcc, 0, v1, vcc
	v_add_co_u32_e32 v6, vcc, s16, v0
	s_mov_b32 s16, 0x6e000
	s_nop 0
	v_addc_co_u32_e32 v7, vcc, 0, v1, vcc
	v_add_co_u32_e32 v8, vcc, s16, v0
	s_mov_b32 s16, 0x82000
	s_nop 0
	v_addc_co_u32_e32 v9, vcc, 0, v1, vcc
	v_add_co_u32_e32 v10, vcc, s62, v0
	s_mov_b32 s28, -2
	s_nop 0
	v_addc_co_u32_e32 v11, vcc, 0, v1, vcc
	v_add_co_u32_e32 v12, vcc, s16, v0
	s_mov_b32 s16, 0x8c000
	s_nop 0
	v_addc_co_u32_e32 v13, vcc, 0, v1, vcc
	v_add_co_u32_e32 v14, vcc, s16, v0
	s_nop 1
	v_addc_co_u32_e32 v15, vcc, 0, v1, vcc
	v_add_co_u32_e32 v0, vcc, s65, v0
	s_nop 1
	v_addc_co_u32_e32 v1, vcc, 0, v1, vcc
	global_load_dword v164, v[2:3], off
	global_load_dword v165, v[4:5], off
	global_load_dword v168, v[6:7], off
	global_load_dword v175, v[8:9], off
	global_load_dword v179, v[10:11], off
	global_load_dword v183, v[12:13], off
	global_load_dword v190, v[14:15], off
	global_load_dword v191, v[0:1], off
	v_add_u32_e32 v0, s26, v130
	v_ashrrev_i32_e32 v1, 31, v0
	v_lshlrev_b64 v[0:1], 11, v[0:1]
	v_lshl_add_u64 v[138:139], v[132:133], 0, v[0:1]
	v_add_u32_e32 v0, s40, v130
	v_ashrrev_i32_e32 v1, 31, v0
	v_lshlrev_b64 v[0:1], 11, v[0:1]
	v_lshl_add_u64 v[140:141], v[134:135], 0, v[0:1]
	v_add_co_u32_e32 v0, vcc, s11, v138
	s_nop 1
	v_addc_co_u32_e32 v1, vcc, 0, v139, vcc
	v_add_co_u32_e32 v2, vcc, s33, v138
	s_nop 1
	v_addc_co_u32_e32 v3, vcc, 0, v139, vcc
	global_load_dwordx4 v[100:103], v[0:1], off offset:128
	global_load_dwordx4 v[104:107], v[2:3], off offset:128
	v_add_co_u32_e32 v0, vcc, 0x30000, v138
	global_load_dwordx4 v[96:99], v[138:139], off offset:128
	global_load_dwordx4 v[108:111], v[140:141], off offset:128
	v_addc_co_u32_e32 v1, vcc, 0, v139, vcc
	v_add_co_u32_e32 v2, vcc, s11, v140
	s_nop 1
	v_addc_co_u32_e32 v3, vcc, 0, v141, vcc
	global_load_dwordx4 v[112:115], v[0:1], off offset:128
	global_load_dwordx4 v[116:119], v[2:3], off offset:128
	v_add_co_u32_e32 v0, vcc, 0x20000, v140
	s_nop 1
	v_addc_co_u32_e32 v1, vcc, 0, v141, vcc
	v_add_co_u32_e32 v2, vcc, 0x30000, v140
	s_nop 1
	v_addc_co_u32_e32 v3, vcc, 0, v141, vcc
	global_load_dwordx4 v[120:123], v[0:1], off offset:128
	global_load_dwordx4 v[124:127], v[2:3], off offset:128
	v_mov_b32_e32 v0, 0
	v_mov_b32_e32 v1, v0
	v_mov_b32_e32 v2, v0
	v_mov_b32_e32 v3, v0
	v_mov_b32_e32 v4, v0
	v_mov_b32_e32 v5, v0
	v_mov_b32_e32 v6, v0
	v_mov_b32_e32 v7, v0
	v_mov_b32_e32 v8, v0
	v_mov_b32_e32 v9, v0
	v_mov_b32_e32 v10, v0
	v_mov_b32_e32 v11, v0
	v_mov_b32_e32 v12, v0
	v_mov_b32_e32 v13, v0
	v_mov_b32_e32 v14, v0
	v_mov_b32_e32 v15, v0
	v_mov_b32_e32 v16, v0
	v_mov_b32_e32 v17, v0
	v_mov_b32_e32 v18, v0
	v_mov_b32_e32 v19, v0
	s_waitcnt vmcnt(40)
	v_mov_b32_e32 v20, v0
	v_mov_b32_e32 v21, v0
	v_mov_b32_e32 v22, v0
	v_mov_b32_e32 v23, v0
	v_mov_b32_e32 v24, v0
	v_mov_b32_e32 v25, v0
	v_mov_b32_e32 v26, v0
	v_mov_b32_e32 v27, v0
	v_mov_b32_e32 v28, v0
	v_mov_b32_e32 v29, v0
	v_mov_b32_e32 v30, v0
	v_mov_b32_e32 v31, v0
	v_mov_b32_e32 v32, v0
	v_mov_b32_e32 v33, v0
	v_mov_b32_e32 v34, v0
	v_mov_b32_e32 v35, v0
	v_mov_b32_e32 v36, v0
	v_mov_b32_e32 v37, v0
	v_mov_b32_e32 v38, v0
	v_mov_b32_e32 v39, v0
	v_mov_b32_e32 v40, v0
	v_mov_b32_e32 v41, v0
	v_mov_b32_e32 v42, v0
	v_mov_b32_e32 v43, v0
	v_mov_b32_e32 v44, v0
	v_mov_b32_e32 v45, v0
	v_mov_b32_e32 v46, v0
	v_mov_b32_e32 v47, v0
	v_mov_b32_e32 v48, v0
	v_mov_b32_e32 v49, v0
	v_mov_b32_e32 v50, v0
	v_mov_b32_e32 v51, v0
	v_mov_b32_e32 v52, v0
	v_mov_b32_e32 v53, v0
	v_mov_b32_e32 v54, v0
	v_mov_b32_e32 v55, v0
	v_mov_b32_e32 v56, v0
	v_mov_b32_e32 v57, v0
	v_mov_b32_e32 v58, v0
	v_mov_b32_e32 v59, v0
	v_mov_b32_e32 v60, v0
	v_mov_b32_e32 v61, v0
	v_mov_b32_e32 v62, v0
	v_mov_b32_e32 v63, v0
	s_waitcnt vmcnt(29)
	ds_write_b128 v156, v[68:71]
	ds_write_b128 v156, v[64:67] offset:4096
	ds_write_b128 v156, v[72:75] offset:8192
	s_waitcnt vmcnt(27)
	ds_write_b128 v156, v[80:83] offset:12288
	ds_write_b128 v156, v[76:79] offset:16384
	s_waitcnt vmcnt(26)
	ds_write_b128 v156, v[84:87] offset:20480
	s_waitcnt vmcnt(25)
	ds_write_b128 v156, v[88:91] offset:24576
	s_waitcnt vmcnt(24)
	ds_write_b128 v156, v[92:95] offset:28672
	s_waitcnt lgkmcnt(0)
	s_barrier

.LBB0_371:
	s_lshl_b32 s2, s40, 7
	s_ashr_i32 s3, s2, 31
	v_lshl_add_u64 v[0:1], s[2:3], 2, v[136:137]
	s_mov_b32 s3, 0xa000
	v_add_co_u32_e32 v2, vcc, s3, v0
	s_mov_b32 s3, 0x14000
	s_nop 0
	v_addc_co_u32_e32 v3, vcc, 0, v1, vcc
	v_add_co_u32_e32 v4, vcc, s3, v0
	s_mov_b32 s3, 0x28000
	s_nop 0
	v_addc_co_u32_e32 v5, vcc, 0, v1, vcc
	v_add_co_u32_e32 v6, vcc, s12, v0
	s_nop 1
	v_addc_co_u32_e32 v7, vcc, 0, v1, vcc
	v_add_co_u32_e32 v8, vcc, s3, v0
	s_mov_b32 s3, 0x32000
	s_nop 0
	v_addc_co_u32_e32 v9, vcc, 0, v1, vcc
	v_add_co_u32_e32 v10, vcc, s3, v0
	s_mov_b32 s3, 0x46000
	s_nop 0
	v_addc_co_u32_e32 v11, vcc, 0, v1, vcc
	v_add_co_u32_e32 v12, vcc, s63, v0
	s_nop 0
	s_nop 0
	v_addc_co_u32_e32 v13, vcc, 0, v1, vcc
	v_add_co_u32_e32 v14, vcc, s3, v0
	s_mov_b32 s3, 0x50000
	s_nop 0
	v_addc_co_u32_e32 v15, vcc, 0, v1, vcc
	global_load_dword v128, v[0:1], off
	global_load_dword v157, v[2:3], off
	global_load_dword v158, v[4:5], off
	global_load_dword v159, v[6:7], off
	global_load_dword v160, v[8:9], off
	global_load_dword v161, v[10:11], off
	global_load_dword v162, v[12:13], off
	global_load_dword v163, v[14:15], off
	v_add_co_u32_e32 v2, vcc, s3, v0
	s_mov_b32 s3, 0x64000
	s_nop 0
	v_addc_co_u32_e32 v3, vcc, 0, v1, vcc
	v_add_co_u32_e32 v4, vcc, s57, v0
	s_lshl_b32 s39, s39, 7
	s_nop 0
	v_addc_co_u32_e32 v5, vcc, 0, v1, vcc
	v_add_co_u32_e32 v6, vcc, s3, v0
	s_mov_b32 s3, 0x6e000
	s_nop 0
	v_addc_co_u32_e32 v7, vcc, 0, v1, vcc
	v_add_co_u32_e32 v8, vcc, s3, v0
	s_mov_b32 s3, 0x82000
	s_nop 0
	v_addc_co_u32_e32 v9, vcc, 0, v1, vcc
	v_add_co_u32_e32 v10, vcc, s62, v0
	s_mov_b32 s24, -2
	s_nop 0
	v_addc_co_u32_e32 v11, vcc, 0, v1, vcc
	v_add_co_u32_e32 v12, vcc, s3, v0
	s_mov_b32 s3, 0x8c000
	s_nop 0
	v_addc_co_u32_e32 v13, vcc, 0, v1, vcc
	v_add_co_u32_e32 v14, vcc, s3, v0
	s_nop 1
	v_addc_co_u32_e32 v15, vcc, 0, v1, vcc
	v_add_co_u32_e32 v0, vcc, s65, v0
	s_nop 1
	v_addc_co_u32_e32 v1, vcc, 0, v1, vcc
	global_load_dword v164, v[2:3], off
	global_load_dword v165, v[4:5], off
	global_load_dword v168, v[6:7], off
	global_load_dword v175, v[8:9], off
	global_load_dword v179, v[10:11], off
	global_load_dword v183, v[12:13], off
	global_load_dword v190, v[14:15], off
	global_load_dword v191, v[0:1], off
	v_add_u32_e32 v0, s2, v130
	v_ashrrev_i32_e32 v1, 31, v0
	v_lshlrev_b64 v[0:1], 11, v[0:1]
	v_lshl_add_u64 v[138:139], v[132:133], 0, v[0:1]
	v_add_u32_e32 v0, s39, v130
	v_ashrrev_i32_e32 v1, 31, v0
	v_lshlrev_b64 v[0:1], 11, v[0:1]
	v_lshl_add_u64 v[140:141], v[134:135], 0, v[0:1]
	v_add_co_u32_e32 v0, vcc, s11, v138
	s_nop 1
	v_addc_co_u32_e32 v1, vcc, 0, v139, vcc
	v_add_co_u32_e32 v2, vcc, s33, v138
	s_nop 1
	v_addc_co_u32_e32 v3, vcc, 0, v139, vcc
	global_load_dwordx4 v[100:103], v[0:1], off offset:128
	global_load_dwordx4 v[104:107], v[2:3], off offset:128
	v_add_co_u32_e32 v0, vcc, 0x30000, v138
	global_load_dwordx4 v[96:99], v[138:139], off offset:128
	global_load_dwordx4 v[108:111], v[140:141], off offset:128
	v_addc_co_u32_e32 v1, vcc, 0, v139, vcc
	v_add_co_u32_e32 v2, vcc, s11, v140
	s_nop 1
	v_addc_co_u32_e32 v3, vcc, 0, v141, vcc
	global_load_dwordx4 v[112:115], v[0:1], off offset:128
	global_load_dwordx4 v[116:119], v[2:3], off offset:128
	v_add_co_u32_e32 v0, vcc, 0x20000, v140
	s_nop 1
	v_addc_co_u32_e32 v1, vcc, 0, v141, vcc
	v_add_co_u32_e32 v2, vcc, 0x30000, v140
	s_nop 1
	v_addc_co_u32_e32 v3, vcc, 0, v141, vcc
	global_load_dwordx4 v[120:123], v[0:1], off offset:128
	global_load_dwordx4 v[124:127], v[2:3], off offset:128
	v_mov_b32_e32 v0, 0
	v_mov_b32_e32 v1, v0
	v_mov_b32_e32 v2, v0
	v_mov_b32_e32 v3, v0
	v_mov_b32_e32 v4, v0
	v_mov_b32_e32 v5, v0
	v_mov_b32_e32 v6, v0
	v_mov_b32_e32 v7, v0
	v_mov_b32_e32 v8, v0
	v_mov_b32_e32 v9, v0
	v_mov_b32_e32 v10, v0
	v_mov_b32_e32 v11, v0
	v_mov_b32_e32 v12, v0
	v_mov_b32_e32 v13, v0
	v_mov_b32_e32 v14, v0
	v_mov_b32_e32 v15, v0
	v_mov_b32_e32 v16, v0
	v_mov_b32_e32 v17, v0
	v_mov_b32_e32 v18, v0
	v_mov_b32_e32 v19, v0
	s_waitcnt vmcnt(40)
	v_mov_b32_e32 v20, v0
	v_mov_b32_e32 v21, v0
	v_mov_b32_e32 v22, v0
	v_mov_b32_e32 v23, v0
	v_mov_b32_e32 v24, v0
	v_mov_b32_e32 v25, v0
	v_mov_b32_e32 v26, v0
	v_mov_b32_e32 v27, v0
	v_mov_b32_e32 v28, v0
	v_mov_b32_e32 v29, v0
	v_mov_b32_e32 v30, v0
	v_mov_b32_e32 v31, v0
	v_mov_b32_e32 v32, v0
	v_mov_b32_e32 v33, v0
	v_mov_b32_e32 v34, v0
	v_mov_b32_e32 v35, v0
	v_mov_b32_e32 v36, v0
	v_mov_b32_e32 v37, v0
	v_mov_b32_e32 v38, v0
	v_mov_b32_e32 v39, v0
	v_mov_b32_e32 v40, v0
	v_mov_b32_e32 v41, v0
	v_mov_b32_e32 v42, v0
	v_mov_b32_e32 v43, v0
	v_mov_b32_e32 v64, v0
	v_mov_b32_e32 v65, v0
	v_mov_b32_e32 v66, v0
	v_mov_b32_e32 v67, v0
	v_mov_b32_e32 v80, v0
	v_mov_b32_e32 v81, v0
	v_mov_b32_e32 v82, v0
	v_mov_b32_e32 v83, v0
	v_mov_b32_e32 v84, v0
	v_mov_b32_e32 v85, v0
	v_mov_b32_e32 v86, v0
	v_mov_b32_e32 v87, v0
	v_mov_b32_e32 v88, v0
	v_mov_b32_e32 v89, v0
	v_mov_b32_e32 v90, v0
	v_mov_b32_e32 v91, v0
	v_mov_b32_e32 v92, v0
	v_mov_b32_e32 v93, v0
	v_mov_b32_e32 v94, v0
	v_mov_b32_e32 v95, v0
	s_waitcnt vmcnt(29)
	ds_write_b128 v156, v[44:47]
	ds_write_b128 v156, v[52:55] offset:4096
	ds_write_b128 v156, v[56:59] offset:8192
	s_waitcnt vmcnt(27)
	ds_write_b128 v156, v[60:63] offset:12288
	ds_write_b128 v156, v[48:51] offset:16384
	s_waitcnt vmcnt(26)
	ds_write_b128 v156, v[72:75] offset:20480
	s_waitcnt vmcnt(25)
	ds_write_b128 v156, v[68:71] offset:24576
	s_waitcnt vmcnt(24)
	ds_write_b128 v156, v[76:79] offset:28672
	s_waitcnt lgkmcnt(0)
	s_barrier

.LBB0_383:
	s_lshl_b32 s2, s25, 7
	s_ashr_i32 s3, s2, 31
	v_lshl_add_u64 v[0:1], s[2:3], 2, v[132:133]
	s_mov_b32 s3, 0xa000
	v_add_co_u32_e32 v2, vcc, s3, v0
	s_mov_b32 s3, 0x14000
	s_nop 0
	v_addc_co_u32_e32 v3, vcc, 0, v1, vcc
	v_add_co_u32_e32 v4, vcc, s3, v0
	s_mov_b32 s3, 0x28000
	s_nop 0
	v_addc_co_u32_e32 v5, vcc, 0, v1, vcc
	v_add_co_u32_e32 v6, vcc, s12, v0
	s_nop 1
	v_addc_co_u32_e32 v7, vcc, 0, v1, vcc
	v_add_co_u32_e32 v8, vcc, s3, v0
	s_mov_b32 s3, 0x32000
	s_nop 0
	v_addc_co_u32_e32 v9, vcc, 0, v1, vcc
	v_add_co_u32_e32 v10, vcc, s3, v0
	s_mov_b32 s3, 0x46000
	s_nop 0
	v_addc_co_u32_e32 v11, vcc, 0, v1, vcc
	v_add_co_u32_e32 v12, vcc, s63, v0
	s_nop 0
	s_nop 0
	v_addc_co_u32_e32 v13, vcc, 0, v1, vcc
	v_add_co_u32_e32 v14, vcc, s3, v0
	s_mov_b32 s3, 0x50000
	s_nop 0
	v_addc_co_u32_e32 v15, vcc, 0, v1, vcc
	global_load_dword v128, v[0:1], off
	global_load_dword v157, v[2:3], off
	global_load_dword v158, v[4:5], off
	global_load_dword v159, v[6:7], off
	global_load_dword v160, v[8:9], off
	global_load_dword v161, v[10:11], off
	global_load_dword v162, v[12:13], off
	global_load_dword v163, v[14:15], off
	v_add_co_u32_e32 v2, vcc, s3, v0
	s_mov_b32 s3, 0x64000
	s_nop 0
	v_addc_co_u32_e32 v3, vcc, 0, v1, vcc
	v_add_co_u32_e32 v4, vcc, s57, v0
	s_lshl_b32 s29, s24, 7
	s_nop 0
	v_addc_co_u32_e32 v5, vcc, 0, v1, vcc
	v_add_co_u32_e32 v6, vcc, s3, v0
	s_mov_b32 s3, 0x6e000
	s_nop 0
	v_addc_co_u32_e32 v7, vcc, 0, v1, vcc
	v_add_co_u32_e32 v8, vcc, s3, v0
	s_mov_b32 s3, 0x82000
	s_nop 0
	v_addc_co_u32_e32 v9, vcc, 0, v1, vcc
	v_add_co_u32_e32 v10, vcc, s62, v0
	s_mov_b32 s24, -2
	s_nop 0
	v_addc_co_u32_e32 v11, vcc, 0, v1, vcc
	v_add_co_u32_e32 v12, vcc, s3, v0
	s_mov_b32 s3, 0x8c000
	s_nop 0
	v_addc_co_u32_e32 v13, vcc, 0, v1, vcc
	v_add_co_u32_e32 v14, vcc, s3, v0
	s_nop 1
	v_addc_co_u32_e32 v15, vcc, 0, v1, vcc
	v_add_co_u32_e32 v0, vcc, s65, v0
	s_nop 1
	v_addc_co_u32_e32 v1, vcc, 0, v1, vcc
	global_load_dword v164, v[2:3], off
	global_load_dword v165, v[4:5], off
	global_load_dword v168, v[6:7], off
	global_load_dword v175, v[8:9], off
	global_load_dword v179, v[10:11], off
	global_load_dword v183, v[12:13], off
	global_load_dword v190, v[14:15], off
	global_load_dword v191, v[0:1], off
	v_add_u32_e32 v0, s2, v130
	v_ashrrev_i32_e32 v1, 31, v0
	v_lshlrev_b64 v[0:1], 11, v[0:1]
	v_lshl_add_u64 v[138:139], v[134:135], 0, v[0:1]
	v_add_u32_e32 v0, s29, v130
	v_ashrrev_i32_e32 v1, 31, v0
	v_lshlrev_b64 v[0:1], 11, v[0:1]
	v_lshl_add_u64 v[140:141], v[136:137], 0, v[0:1]
	v_add_co_u32_e32 v0, vcc, s11, v138
	s_nop 1
	v_addc_co_u32_e32 v1, vcc, 0, v139, vcc
	v_add_co_u32_e32 v2, vcc, s33, v138
	s_nop 1
	v_addc_co_u32_e32 v3, vcc, 0, v139, vcc
	global_load_dwordx4 v[100:103], v[0:1], off offset:128
	global_load_dwordx4 v[104:107], v[2:3], off offset:128
	v_add_co_u32_e32 v0, vcc, 0x30000, v138
	global_load_dwordx4 v[96:99], v[138:139], off offset:128
	global_load_dwordx4 v[108:111], v[140:141], off offset:128
	v_addc_co_u32_e32 v1, vcc, 0, v139, vcc
	v_add_co_u32_e32 v2, vcc, s11, v140
	s_nop 1
	v_addc_co_u32_e32 v3, vcc, 0, v141, vcc
	global_load_dwordx4 v[112:115], v[0:1], off offset:128
	global_load_dwordx4 v[116:119], v[2:3], off offset:128
	v_add_co_u32_e32 v0, vcc, 0x20000, v140
	s_nop 1
	v_addc_co_u32_e32 v1, vcc, 0, v141, vcc
	v_add_co_u32_e32 v2, vcc, 0x30000, v140
	s_nop 1
	v_addc_co_u32_e32 v3, vcc, 0, v141, vcc
	global_load_dwordx4 v[120:123], v[0:1], off offset:128
	global_load_dwordx4 v[124:127], v[2:3], off offset:128
	v_mov_b32_e32 v0, 0
	v_mov_b32_e32 v1, v0
	v_mov_b32_e32 v2, v0
	v_mov_b32_e32 v3, v0
	v_mov_b32_e32 v4, v0
	v_mov_b32_e32 v5, v0
	v_mov_b32_e32 v6, v0
	v_mov_b32_e32 v7, v0
	v_mov_b32_e32 v8, v0
	v_mov_b32_e32 v9, v0
	v_mov_b32_e32 v10, v0
	v_mov_b32_e32 v11, v0
	v_mov_b32_e32 v12, v0
	v_mov_b32_e32 v13, v0
	v_mov_b32_e32 v14, v0
	v_mov_b32_e32 v15, v0
	v_mov_b32_e32 v16, v0
	v_mov_b32_e32 v17, v0
	v_mov_b32_e32 v18, v0
	v_mov_b32_e32 v19, v0
	s_waitcnt vmcnt(40)
	v_mov_b32_e32 v20, v0
	v_mov_b32_e32 v21, v0
	v_mov_b32_e32 v22, v0
	v_mov_b32_e32 v23, v0
	v_mov_b32_e32 v24, v0
	v_mov_b32_e32 v25, v0
	v_mov_b32_e32 v26, v0
	v_mov_b32_e32 v27, v0
	v_mov_b32_e32 v28, v0
	v_mov_b32_e32 v29, v0
	v_mov_b32_e32 v30, v0
	v_mov_b32_e32 v31, v0
	v_mov_b32_e32 v32, v0
	v_mov_b32_e32 v33, v0
	v_mov_b32_e32 v34, v0
	v_mov_b32_e32 v35, v0
	v_mov_b32_e32 v36, v0
	v_mov_b32_e32 v37, v0
	v_mov_b32_e32 v38, v0
	v_mov_b32_e32 v39, v0
	v_mov_b32_e32 v40, v0
	v_mov_b32_e32 v41, v0
	v_mov_b32_e32 v42, v0
	v_mov_b32_e32 v43, v0
	v_mov_b32_e32 v44, v0
	v_mov_b32_e32 v45, v0
	v_mov_b32_e32 v46, v0
	v_mov_b32_e32 v47, v0
	v_mov_b32_e32 v48, v0
	v_mov_b32_e32 v49, v0
	v_mov_b32_e32 v50, v0
	v_mov_b32_e32 v51, v0
	v_mov_b32_e32 v52, v0
	v_mov_b32_e32 v53, v0
	v_mov_b32_e32 v54, v0
	v_mov_b32_e32 v55, v0
	v_mov_b32_e32 v56, v0
	v_mov_b32_e32 v57, v0
	v_mov_b32_e32 v58, v0
	v_mov_b32_e32 v59, v0
	v_mov_b32_e32 v60, v0
	v_mov_b32_e32 v61, v0
	v_mov_b32_e32 v62, v0
	v_mov_b32_e32 v63, v0
	s_waitcnt vmcnt(29)
	ds_write_b128 v156, v[68:71]
	ds_write_b128 v156, v[64:67] offset:4096
	ds_write_b128 v156, v[72:75] offset:8192
	s_waitcnt vmcnt(27)
	ds_write_b128 v156, v[80:83] offset:12288
	ds_write_b128 v156, v[76:79] offset:16384
	s_waitcnt vmcnt(26)
	ds_write_b128 v156, v[84:87] offset:20480
	s_waitcnt vmcnt(25)
	ds_write_b128 v156, v[88:91] offset:24576
	s_waitcnt vmcnt(24)
	ds_write_b128 v156, v[92:95] offset:28672
	s_waitcnt lgkmcnt(0)
	s_barrier

.LBB0_390:
	v_readlane_b32 s0, v250, 13
	v_readlane_b32 s1, v250, 14
	s_and_b64 vcc, exec, s[0:1]
	s_cbranch_vccz .LBB0_425
	s_lshl_b32 s0, s69, 21
	v_readlane_b32 s1, v250, 63
	s_add_u32 s2, s1, s0
	v_readlane_b32 s0, v251, 0
	s_waitcnt vmcnt(21)
	v_mov_b32_e32 v44, v166
	s_addc_u32 s3, s0, 0
	v_readlane_b32 s0, v251, 5
	v_ashrrev_i32_e32 v106, 3, v44
	v_lshlrev_b32_e32 v2, 3, v44
	v_add_u32_e32 v0, s0, v106
	s_waitcnt lgkmcnt(0)
	v_ashrrev_i32_e32 v1, 31, v0
	v_readlane_b32 s0, v251, 20
	v_lshlrev_b64 v[0:1], 11, v[0:1]
	v_readlane_b32 s1, v251, 21
	v_and_b32_e32 v96, 56, v2
	v_lshlrev_b32_e32 v128, 1, v96
	v_lshl_add_u64 v[0:1], s[0:1], 0, v[0:1]
	v_lshl_add_u64 v[98:99], v[0:1], 0, v[128:129]
	v_readlane_b32 s0, v251, 6
	s_waitcnt vmcnt(11)
	v_add_co_u32_e32 v32, vcc, s11, v98
	v_add_u32_e32 v0, s0, v106
	s_nop 0
	v_addc_co_u32_e32 v33, vcc, 0, v99, vcc
	v_ashrrev_i32_e32 v1, 31, v0
	v_add_co_u32_e32 v34, vcc, s33, v98
	v_lshlrev_b64 v[0:1], 11, v[0:1]
	s_nop 0
	v_addc_co_u32_e32 v35, vcc, 0, v99, vcc
	v_lshl_add_u64 v[0:1], s[2:3], 0, v[0:1]
	v_add_co_u32_e32 v36, vcc, s59, v98
	v_lshl_add_u64 v[100:101], v[0:1], 0, v[128:129]
	s_nop 0
	v_addc_co_u32_e32 v37, vcc, 0, v99, vcc
	v_add_co_u32_e32 v38, vcc, s11, v100
	global_load_dwordx4 v[0:3], v[32:33], off
	global_load_dwordx4 v[4:7], v[34:35], off
	v_addc_co_u32_e32 v39, vcc, 0, v101, vcc
	v_add_co_u32_e32 v40, vcc, s33, v100
	global_load_dwordx4 v[8:11], v[98:99], off
	global_load_dwordx4 v[12:15], v[100:101], off
	v_addc_co_u32_e32 v41, vcc, 0, v101, vcc
	v_add_co_u32_e32 v42, vcc, s59, v100
	global_load_dwordx4 v[16:19], v[36:37], off
	global_load_dwordx4 v[20:23], v[38:39], off
	v_addc_co_u32_e32 v43, vcc, 0, v101, vcc
	global_load_dwordx4 v[24:27], v[40:41], off
	global_load_dwordx4 v[28:31], v[42:43], off
	global_load_dwordx4 v[60:63], v[32:33], off offset:128
	global_load_dwordx4 v[64:67], v[34:35], off offset:128
	global_load_dwordx4 v[56:59], v[98:99], off offset:128
	global_load_dwordx4 v[68:71], v[100:101], off offset:128
	global_load_dwordx4 v[72:75], v[36:37], off offset:128
	global_load_dwordx4 v[76:79], v[38:39], off offset:128
	global_load_dwordx4 v[80:83], v[40:41], off offset:128
	global_load_dwordx4 v[84:87], v[42:43], off offset:128
	v_ashrrev_i32_e32 v46, 1, v44
	v_lshlrev_b32_e32 v47, 4, v44
	v_and_b32_e32 v107, 15, v44
	v_lshrrev_b32_e32 v45, 4, v44
	v_bfe_u32 v97, v44, 4, 2
	v_bfe_u32 v102, v44, 6, 1
	s_waitcnt vmcnt(25)
	v_bfe_u32 v48, v44, 1, 3
	v_and_b32_e32 v108, 0xffffffc0, v46
	v_lshlrev_b32_e32 v46, 7, v106
	v_xor_b32_e32 v44, v47, v44
	s_movk_i32 s0, 0x70
	v_and_or_b32 v44, v44, s0, v46
	v_add_u32_e32 v109, 0, v44
	v_lshlrev_b32_e32 v47, 7, v107
	v_or_b32_e32 v46, v108, v107
	v_lshl_or_b32 v47, v102, 13, v47
	v_lshl_add_u32 v103, v46, 7, 0
	v_add_u32_e32 v104, 0, v47
	s_mov_b32 s1, -2
	s_waitcnt vmcnt(13)
	ds_write_b128 v109, v[8:11]
	s_waitcnt vmcnt(12)
	ds_write_b128 v109, v[12:15] offset:16384
	ds_write_b128 v109, v[0:3] offset:4096
	ds_write_b128 v109, v[4:7] offset:8192
	s_waitcnt vmcnt(11)
	ds_write_b128 v109, v[16:19] offset:12288
	s_waitcnt vmcnt(10)
	ds_write_b128 v109, v[20:23] offset:20480
	s_waitcnt vmcnt(9)
	ds_write_b128 v109, v[24:27] offset:24576
	s_waitcnt vmcnt(8)
	ds_write_b128 v109, v[28:31] offset:28672
	v_bitop3_b32 v0, v48, v45, 3 bitop3:0x78
	v_lshlrev_b32_e32 v105, 4, v0
	v_bitop3_b32 v0, v97, v48, 4 bitop3:0x36
	v_lshlrev_b32_e32 v114, 4, v0
	v_mov_b32_e32 v0, 0
	v_mov_b32_e32 v1, v0
	v_mov_b32_e32 v2, v0
	v_mov_b32_e32 v3, v0
	v_mov_b32_e32 v4, v0
	v_mov_b32_e32 v5, v0
	v_mov_b32_e32 v6, v0
	v_mov_b32_e32 v7, v0
	v_mov_b32_e32 v8, v0
	v_mov_b32_e32 v9, v0
	v_mov_b32_e32 v10, v0
	v_mov_b32_e32 v11, v0
	v_mov_b32_e32 v12, v0
	v_mov_b32_e32 v13, v0
	v_mov_b32_e32 v14, v0
	v_mov_b32_e32 v15, v0
	v_mov_b32_e32 v16, v0
	v_mov_b32_e32 v17, v0
	v_mov_b32_e32 v18, v0
	v_mov_b32_e32 v19, v0
	v_mov_b32_e32 v20, v0
	v_mov_b32_e32 v21, v0
	v_mov_b32_e32 v22, v0
	v_mov_b32_e32 v23, v0
	v_mov_b32_e32 v24, v0
	v_mov_b32_e32 v25, v0
	v_mov_b32_e32 v26, v0
	v_mov_b32_e32 v27, v0
	v_mov_b32_e32 v28, v0
	v_mov_b32_e32 v29, v0
	v_mov_b32_e32 v30, v0
	v_mov_b32_e32 v31, v0
	v_mov_b32_e32 v32, v0
	v_mov_b32_e32 v33, v0
	v_mov_b32_e32 v34, v0
	v_mov_b32_e32 v35, v0
	v_mov_b32_e32 v36, v0
	v_mov_b32_e32 v37, v0
	v_mov_b32_e32 v38, v0
	v_mov_b32_e32 v39, v0
	v_mov_b32_e32 v40, v0
	v_mov_b32_e32 v41, v0
	v_mov_b32_e32 v42, v0
	v_mov_b32_e32 v43, v0
	v_mov_b32_e32 v44, v0
	v_mov_b32_e32 v45, v0
	v_mov_b32_e32 v46, v0
	v_mov_b32_e32 v47, v0
	v_mov_b32_e32 v48, v0
	v_mov_b32_e32 v49, v0
	v_mov_b32_e32 v50, v0
	v_mov_b32_e32 v51, v0
	v_mov_b32_e32 v52, v0
	v_mov_b32_e32 v53, v0
	v_mov_b32_e32 v54, v0
	v_mov_b32_e32 v55, v0
	v_mov_b32_e32 v88, v0
	v_mov_b32_e32 v89, v0
	v_mov_b32_e32 v90, v0
	v_mov_b32_e32 v91, v0
	v_mov_b32_e32 v92, v0
	v_mov_b32_e32 v93, v0
	v_mov_b32_e32 v94, v0
	v_mov_b32_e32 v95, v0
	s_waitcnt lgkmcnt(0)
	s_barrier

.LBB0_579:
	s_and_b64 vcc, exec, s[0:1]
	s_cbranch_vccz .LBB0_616
	v_readlane_b32 s0, v250, 13
	v_readlane_b32 s1, v250, 14
	s_and_b64 vcc, exec, s[0:1]
	s_cbranch_vccz .LBB0_615
	s_lshl_b32 s0, s69, 23
	v_readlane_b32 s1, v250, 59
	s_add_u32 s2, s1, s0
	v_readlane_b32 s0, v250, 60
	s_waitcnt vmcnt(21)
	v_mov_b32_e32 v44, v166
	s_addc_u32 s3, s0, 0
	v_readlane_b32 s0, v251, 5
	v_ashrrev_i32_e32 v106, 3, v44
	v_lshlrev_b32_e32 v2, 3, v44
	v_add_u32_e32 v0, s0, v106
	s_waitcnt lgkmcnt(0)
	v_ashrrev_i32_e32 v1, 31, v0
	v_lshlrev_b64 v[0:1], 13, v[0:1]
	v_and_b32_e32 v96, 56, v2
	v_lshl_add_u64 v[0:1], s[30:31], 0, v[0:1]
	v_lshlrev_b32_e32 v128, 1, v96
	v_lshl_add_u64 v[98:99], v[0:1], 0, v[128:129]
	v_readlane_b32 s0, v251, 6
	s_waitcnt vmcnt(11)
	v_add_co_u32_e32 v32, vcc, s7, v98
	v_add_u32_e32 v0, s0, v106
	s_nop 0
	v_addc_co_u32_e32 v33, vcc, 0, v99, vcc
	v_ashrrev_i32_e32 v1, 31, v0
	v_add_co_u32_e32 v34, vcc, s52, v98
	v_lshlrev_b64 v[0:1], 13, v[0:1]
	s_nop 0
	v_addc_co_u32_e32 v35, vcc, 0, v99, vcc
	v_lshl_add_u64 v[0:1], s[2:3], 0, v[0:1]
	v_add_co_u32_e32 v36, vcc, s34, v98
	v_lshl_add_u64 v[100:101], v[0:1], 0, v[128:129]
	s_nop 0
	v_addc_co_u32_e32 v37, vcc, 0, v99, vcc
	v_add_co_u32_e32 v38, vcc, s7, v100
	global_load_dwordx4 v[0:3], v[32:33], off
	global_load_dwordx4 v[4:7], v[34:35], off
	v_addc_co_u32_e32 v39, vcc, 0, v101, vcc
	v_add_co_u32_e32 v40, vcc, s52, v100
	global_load_dwordx4 v[8:11], v[98:99], off
	global_load_dwordx4 v[12:15], v[100:101], off
	v_addc_co_u32_e32 v41, vcc, 0, v101, vcc
	v_add_co_u32_e32 v42, vcc, s34, v100
	global_load_dwordx4 v[16:19], v[36:37], off
	global_load_dwordx4 v[20:23], v[38:39], off
	v_addc_co_u32_e32 v43, vcc, 0, v101, vcc
	global_load_dwordx4 v[24:27], v[40:41], off
	global_load_dwordx4 v[28:31], v[42:43], off
	global_load_dwordx4 v[60:63], v[32:33], off offset:128
	global_load_dwordx4 v[64:67], v[34:35], off offset:128
	global_load_dwordx4 v[56:59], v[98:99], off offset:128
	global_load_dwordx4 v[68:71], v[100:101], off offset:128
	global_load_dwordx4 v[72:75], v[36:37], off offset:128
	global_load_dwordx4 v[76:79], v[38:39], off offset:128
	global_load_dwordx4 v[80:83], v[40:41], off offset:128
	global_load_dwordx4 v[84:87], v[42:43], off offset:128
	v_ashrrev_i32_e32 v46, 1, v44
	v_lshlrev_b32_e32 v47, 4, v44
	v_and_b32_e32 v107, 15, v44
	v_lshrrev_b32_e32 v45, 4, v44
	v_bfe_u32 v97, v44, 4, 2
	v_bfe_u32 v102, v44, 6, 1
	s_waitcnt vmcnt(25)
	v_bfe_u32 v48, v44, 1, 3
	v_and_b32_e32 v108, 0xffffffc0, v46
	v_lshlrev_b32_e32 v46, 7, v106
	v_xor_b32_e32 v44, v47, v44
	s_movk_i32 s0, 0x70
	v_and_or_b32 v44, v44, s0, v46
	v_add_u32_e32 v109, 0, v44
	v_lshlrev_b32_e32 v47, 7, v107
	v_or_b32_e32 v46, v108, v107
	v_lshl_or_b32 v47, v102, 13, v47
	v_lshl_add_u32 v103, v46, 7, 0
	v_add_u32_e32 v104, 0, v47
	s_mov_b32 s1, -2
	s_waitcnt vmcnt(13)
	ds_write_b128 v109, v[8:11]
	s_waitcnt vmcnt(12)
	ds_write_b128 v109, v[12:15] offset:16384
	ds_write_b128 v109, v[0:3] offset:4096
	ds_write_b128 v109, v[4:7] offset:8192
	s_waitcnt vmcnt(11)
	ds_write_b128 v109, v[16:19] offset:12288
	s_waitcnt vmcnt(10)
	ds_write_b128 v109, v[20:23] offset:20480
	s_waitcnt vmcnt(9)
	ds_write_b128 v109, v[24:27] offset:24576
	s_waitcnt vmcnt(8)
	ds_write_b128 v109, v[28:31] offset:28672
	v_bitop3_b32 v0, v48, v45, 3 bitop3:0x78
	v_lshlrev_b32_e32 v105, 4, v0
	v_bitop3_b32 v0, v97, v48, 4 bitop3:0x36
	v_lshlrev_b32_e32 v114, 4, v0
	v_mov_b32_e32 v0, 0
	v_mov_b32_e32 v1, v0
	v_mov_b32_e32 v2, v0
	v_mov_b32_e32 v3, v0
	v_mov_b32_e32 v4, v0
	v_mov_b32_e32 v5, v0
	v_mov_b32_e32 v6, v0
	v_mov_b32_e32 v7, v0
	v_mov_b32_e32 v8, v0
	v_mov_b32_e32 v9, v0
	v_mov_b32_e32 v10, v0
	v_mov_b32_e32 v11, v0
	v_mov_b32_e32 v12, v0
	v_mov_b32_e32 v13, v0
	v_mov_b32_e32 v14, v0
	v_mov_b32_e32 v15, v0
	v_mov_b32_e32 v16, v0
	v_mov_b32_e32 v17, v0
	v_mov_b32_e32 v18, v0
	v_mov_b32_e32 v19, v0
	v_mov_b32_e32 v20, v0
	v_mov_b32_e32 v21, v0
	v_mov_b32_e32 v22, v0
	v_mov_b32_e32 v23, v0
	v_mov_b32_e32 v24, v0
	v_mov_b32_e32 v25, v0
	v_mov_b32_e32 v26, v0
	v_mov_b32_e32 v27, v0
	v_mov_b32_e32 v28, v0
	v_mov_b32_e32 v29, v0
	v_mov_b32_e32 v30, v0
	v_mov_b32_e32 v31, v0
	v_mov_b32_e32 v32, v0
	v_mov_b32_e32 v33, v0
	v_mov_b32_e32 v34, v0
	v_mov_b32_e32 v35, v0
	v_mov_b32_e32 v36, v0
	v_mov_b32_e32 v37, v0
	v_mov_b32_e32 v38, v0
	v_mov_b32_e32 v39, v0
	v_mov_b32_e32 v40, v0
	v_mov_b32_e32 v41, v0
	v_mov_b32_e32 v42, v0
	v_mov_b32_e32 v43, v0
	v_mov_b32_e32 v44, v0
	v_mov_b32_e32 v45, v0
	v_mov_b32_e32 v46, v0
	v_mov_b32_e32 v47, v0
	v_mov_b32_e32 v48, v0
	v_mov_b32_e32 v49, v0
	v_mov_b32_e32 v50, v0
	v_mov_b32_e32 v51, v0
	v_mov_b32_e32 v52, v0
	v_mov_b32_e32 v53, v0
	v_mov_b32_e32 v54, v0
	v_mov_b32_e32 v55, v0
	v_mov_b32_e32 v88, v0
	v_mov_b32_e32 v89, v0
	v_mov_b32_e32 v90, v0
	v_mov_b32_e32 v91, v0
	v_mov_b32_e32 v92, v0
	v_mov_b32_e32 v93, v0
	v_mov_b32_e32 v94, v0
	v_mov_b32_e32 v95, v0
	s_waitcnt lgkmcnt(0)
	s_barrier

.LBB0_595:
	s_ashr_i32 s24, s28, 31
	s_lshr_b32 s24, s24, 27
	s_add_i32 s24, s28, s24
	s_and_b32 s25, s24, 0xffffffe0
	s_sub_i32 s25, s28, s25
	s_lshl_b32 s24, s24, 4
	s_lshl_b32 s29, s25, 7
	s_and_b32 s24, s24, 0xfffffe00
	s_and_b32 s29, s29, 0x180
	s_or_b32 s24, s29, s24
	v_add_u32_e32 v0, s24, v106
	s_lshl_b32 s25, s25, 5
	s_waitcnt lgkmcnt(0)
	v_ashrrev_i32_e32 v1, 31, v0
	s_and_b32 s25, s25, 0xffffff80
	v_lshlrev_b64 v[0:1], 13, v[0:1]
	v_lshl_add_u64 v[100:101], v[96:97], 0, v[0:1]
	v_add_u32_e32 v0, s25, v106
	v_ashrrev_i32_e32 v1, 31, v0
	v_lshlrev_b64 v[0:1], 13, v[0:1]
	v_lshl_add_u64 v[102:103], v[98:99], 0, v[0:1]
	v_add_co_u32_e32 v0, vcc, s7, v100
	s_mov_b32 s42, -2
	s_nop 0
	v_addc_co_u32_e32 v1, vcc, 0, v101, vcc
	v_add_co_u32_e32 v2, vcc, s52, v100
	s_nop 1
	v_addc_co_u32_e32 v3, vcc, 0, v101, vcc
	v_add_co_u32_e32 v4, vcc, s34, v100
	global_load_dwordx4 v[20:23], v[0:1], off
	global_load_dwordx4 v[24:27], v[2:3], off
	v_addc_co_u32_e32 v5, vcc, 0, v101, vcc
	v_add_co_u32_e32 v6, vcc, s52, v102
	global_load_dwordx4 v[28:31], v[100:101], off
	global_load_dwordx4 v[32:35], v[102:103], off
	v_addc_co_u32_e32 v7, vcc, 0, v103, vcc
	v_add_co_u32_e32 v8, vcc, s34, v102
	s_nop 1
	v_addc_co_u32_e32 v9, vcc, 0, v103, vcc
	v_add_co_u32_e32 v10, vcc, s7, v102
	global_load_dwordx4 v[36:39], v[6:7], off
	global_load_dwordx4 v[40:43], v[8:9], off
	v_addc_co_u32_e32 v11, vcc, 0, v103, vcc
	global_load_dwordx4 v[44:47], v[4:5], off
	global_load_dwordx4 v[48:51], v[10:11], off
	global_load_dwordx4 v[60:63], v[0:1], off offset:128
	global_load_dwordx4 v[64:67], v[2:3], off offset:128
	global_load_dwordx4 v[52:55], v[100:101], off offset:128
	global_load_dwordx4 v[68:71], v[102:103], off offset:128
	global_load_dwordx4 v[72:75], v[4:5], off offset:128
	global_load_dwordx4 v[76:79], v[10:11], off offset:128
	global_load_dwordx4 v[80:83], v[6:7], off offset:128
	global_load_dwordx4 v[84:87], v[8:9], off offset:128
	v_mov_b32_e32 v0, 0
	v_mov_b32_e32 v1, v0
	v_mov_b32_e32 v2, v0
	v_mov_b32_e32 v3, v0
	v_mov_b32_e32 v4, v0
	v_mov_b32_e32 v5, v0
	v_mov_b32_e32 v6, v0
	v_mov_b32_e32 v7, v0
	v_mov_b32_e32 v8, v0
	v_mov_b32_e32 v9, v0
	v_mov_b32_e32 v10, v0
	v_mov_b32_e32 v11, v0
	v_mov_b32_e32 v12, v0
	v_mov_b32_e32 v13, v0
	v_mov_b32_e32 v14, v0
	v_mov_b32_e32 v15, v0
	v_mov_b32_e32 v16, v0
	v_mov_b32_e32 v17, v0
	v_mov_b32_e32 v18, v0
	v_mov_b32_e32 v19, v0
	v_mov_b32_e32 v56, v0
	v_mov_b32_e32 v57, v0
	v_mov_b32_e32 v58, v0
	v_mov_b32_e32 v59, v0
	v_mov_b32_e32 v88, v0
	v_mov_b32_e32 v89, v0
	v_mov_b32_e32 v90, v0
	v_mov_b32_e32 v91, v0
	v_mov_b32_e32 v92, v0
	v_mov_b32_e32 v93, v0
	v_mov_b32_e32 v94, v0
	v_mov_b32_e32 v95, v0
	s_waitcnt vmcnt(13)
	ds_write_b128 v109, v[28:31]
	s_waitcnt vmcnt(12)
	ds_write_b128 v109, v[32:35] offset:16384
	s_waitcnt vmcnt(11)
	ds_write_b128 v109, v[36:39] offset:24576
	s_waitcnt vmcnt(10)
	ds_write_b128 v109, v[40:43] offset:28672
	ds_write_b128 v109, v[20:23] offset:4096
	ds_write_b128 v109, v[24:27] offset:8192
	s_waitcnt vmcnt(9)
	ds_write_b128 v109, v[44:47] offset:12288
	s_waitcnt vmcnt(8)
	ds_write_b128 v109, v[48:51] offset:20480
	v_mov_b32_e32 v20, v0
	v_mov_b32_e32 v21, v0
	v_mov_b32_e32 v22, v0
	v_mov_b32_e32 v23, v0
	v_mov_b32_e32 v24, v0
	v_mov_b32_e32 v25, v0
	v_mov_b32_e32 v26, v0
	v_mov_b32_e32 v27, v0
	v_mov_b32_e32 v28, v0
	v_mov_b32_e32 v29, v0
	v_mov_b32_e32 v30, v0
	v_mov_b32_e32 v31, v0
	v_mov_b32_e32 v32, v0
	v_mov_b32_e32 v33, v0
	v_mov_b32_e32 v34, v0
	v_mov_b32_e32 v35, v0
	v_mov_b32_e32 v36, v0
	v_mov_b32_e32 v37, v0
	v_mov_b32_e32 v38, v0
	v_mov_b32_e32 v39, v0
	v_mov_b32_e32 v40, v0
	v_mov_b32_e32 v41, v0
	v_mov_b32_e32 v42, v0
	v_mov_b32_e32 v43, v0
	v_mov_b32_e32 v44, v0
	v_mov_b32_e32 v45, v0
	v_mov_b32_e32 v46, v0
	v_mov_b32_e32 v47, v0
	v_mov_b32_e32 v48, v0
	v_mov_b32_e32 v49, v0
	v_mov_b32_e32 v50, v0
	v_mov_b32_e32 v51, v0
	s_waitcnt lgkmcnt(0)
	s_barrier

.LBB0_606:
	s_andn2_b64 vcc, exec, s[24:25]
	s_cbranch_vccnz .LBB0_615
	v_readlane_b32 s16, v251, 16
	v_readlane_b32 s17, v251, 17
	s_andn2_b64 vcc, exec, s[16:17]
	s_cbranch_vccnz .LBB0_615
	v_mov_b32_e32 v0, v166
	s_movk_i32 s16, 0x70
	s_waitcnt lgkmcnt(0)
	v_ashrrev_i32_e32 v1, 1, v0
	v_ashrrev_i32_e32 v2, 3, v0
	v_lshlrev_b32_e32 v3, 4, v0
	v_and_b32_e32 v86, 0xffffffe0, v1
	v_lshlrev_b32_e32 v1, 7, v2
	v_xor_b32_e32 v4, v3, v0
	v_and_or_b32 v28, v4, s16, v1
	v_readlane_b32 s16, v251, 18
	v_and_b32_e32 v85, 15, v0
	v_lshrrev_b32_e32 v40, 4, v0
	v_bfe_u32 v84, v0, 4, 2
	v_bfe_u32 v41, v0, 1, 3
	v_add_u32_e32 v0, s16, v2
	v_ashrrev_i32_e32 v1, 31, v0
	v_lshlrev_b64 v[0:1], 13, v[0:1]
	v_lshl_add_u64 v[0:1], s[30:31], 0, v[0:1]
	v_and_b32_e32 v128, 0x70, v3
	v_lshl_add_u64 v[80:81], v[0:1], 0, v[128:129]
	v_add_co_u32_e32 v24, vcc, s7, v80
	v_readlane_b32 s16, v251, 19
	s_nop 0
	v_addc_co_u32_e32 v25, vcc, 0, v81, vcc
	v_add_u32_e32 v0, s16, v2
	v_add_co_u32_e32 v26, vcc, s52, v80
	v_ashrrev_i32_e32 v1, 31, v0
	s_nop 0
	v_addc_co_u32_e32 v27, vcc, 0, v81, vcc
	v_lshlrev_b64 v[0:1], 13, v[0:1]
	v_add_co_u32_e32 v36, vcc, s34, v80
	v_lshl_add_u64 v[0:1], s[2:3], 0, v[0:1]
	s_nop 0
	v_addc_co_u32_e32 v37, vcc, 0, v81, vcc
	v_lshl_add_u64 v[82:83], v[0:1], 0, v[128:129]
	global_load_dwordx4 v[0:3], v[80:81], off
	global_load_dwordx4 v[4:7], v[24:25], off
	global_load_dwordx4 v[8:11], v[26:27], off
	global_load_dwordx4 v[12:15], v[36:37], off
	global_load_dwordx4 v[16:19], v[82:83], off
	v_add_co_u32_e32 v38, vcc, s7, v82
	v_add_u32_e32 v87, 0, v28
	s_nop 0
	v_addc_co_u32_e32 v39, vcc, 0, v83, vcc
	global_load_dwordx4 v[20:23], v[38:39], off
	v_or_b32_e32 v42, v86, v85
	v_lshl_add_u32 v88, v42, 7, 0
	v_lshl_add_u32 v89, v85, 7, 0
	s_mov_b32 s3, -2
	s_waitcnt vmcnt(5)
	ds_write_b128 v87, v[0:3]
	s_waitcnt vmcnt(4)
	ds_write_b128 v87, v[4:7] offset:4096
	s_waitcnt vmcnt(3)
	ds_write_b128 v87, v[8:11] offset:8192
	s_waitcnt vmcnt(2)
	ds_write_b128 v87, v[12:15] offset:12288
	s_waitcnt vmcnt(1)
	ds_write_b128 v87, v[16:19] offset:16384
	s_waitcnt vmcnt(0)
	ds_write_b128 v87, v[20:23] offset:20480
	global_load_dwordx4 v[28:31], v[80:81], off offset:128
	global_load_dwordx4 v[32:35], v[24:25], off offset:128
	s_nop 0
	global_load_dwordx4 v[24:27], v[26:27], off offset:128
	s_nop 0
	global_load_dwordx4 v[20:23], v[36:37], off offset:128
	global_load_dwordx4 v[16:19], v[82:83], off offset:128
	global_load_dwordx4 v[12:15], v[38:39], off offset:128
	v_bitop3_b32 v0, v41, v40, 3 bitop3:0x78
	v_lshlrev_b32_e32 v90, 4, v0
	v_bitop3_b32 v0, v84, v41, 4 bitop3:0x36
	v_lshlrev_b32_e32 v91, 4, v0
	v_mov_b32_e32 v0, 0
	v_mov_b32_e32 v1, v0
	v_mov_b32_e32 v2, v0
	v_mov_b32_e32 v3, v0
	v_mov_b32_e32 v4, v0
	v_mov_b32_e32 v5, v0
	v_mov_b32_e32 v6, v0
	v_mov_b32_e32 v7, v0
	v_mov_b32_e32 v8, v0
	v_mov_b32_e32 v9, v0
	v_mov_b32_e32 v10, v0
	v_mov_b32_e32 v11, v0
	v_mov_b32_e32 v36, v0
	v_mov_b32_e32 v37, v0
	v_mov_b32_e32 v38, v0
	v_mov_b32_e32 v39, v0
	v_mov_b32_e32 v40, v0
	v_mov_b32_e32 v41, v0
	v_mov_b32_e32 v42, v0
	v_mov_b32_e32 v43, v0
	v_mov_b32_e32 v52, v0
	v_mov_b32_e32 v53, v0
	v_mov_b32_e32 v54, v0
	v_mov_b32_e32 v55, v0
	v_mov_b32_e32 v68, v0
	v_mov_b32_e32 v69, v0
	v_mov_b32_e32 v70, v0
	v_mov_b32_e32 v71, v0
	v_mov_b32_e32 v76, v0
	v_mov_b32_e32 v77, v0
	v_mov_b32_e32 v78, v0
	v_mov_b32_e32 v79, v0
	s_waitcnt lgkmcnt(0)
	s_barrier

.LBB0_627:
	s_lshl_b32 s2, s49, 7
	s_ashr_i32 s3, s2, 31
	v_lshl_add_u64 v[0:1], s[2:3], 2, v[136:137]
	s_mov_b32 s3, 0xa000
	v_add_co_u32_e32 v2, vcc, s3, v0
	s_mov_b32 s3, 0x14000
	s_nop 0
	v_addc_co_u32_e32 v3, vcc, 0, v1, vcc
	v_add_co_u32_e32 v4, vcc, s3, v0
	s_mov_b32 s3, 0x28000
	s_nop 0
	v_addc_co_u32_e32 v5, vcc, 0, v1, vcc
	v_add_co_u32_e32 v6, vcc, s12, v0
	s_nop 1
	v_addc_co_u32_e32 v7, vcc, 0, v1, vcc
	v_add_co_u32_e32 v8, vcc, s3, v0
	s_mov_b32 s3, 0x32000
	s_nop 0
	v_addc_co_u32_e32 v9, vcc, 0, v1, vcc
	v_add_co_u32_e32 v10, vcc, s3, v0
	s_mov_b32 s3, 0x46000
	s_nop 0
	v_addc_co_u32_e32 v11, vcc, 0, v1, vcc
	v_add_co_u32_e32 v12, vcc, s63, v0
	s_nop 0
	s_nop 0
	v_addc_co_u32_e32 v13, vcc, 0, v1, vcc
	v_add_co_u32_e32 v14, vcc, s3, v0
	s_mov_b32 s3, 0x50000
	s_nop 0
	v_addc_co_u32_e32 v15, vcc, 0, v1, vcc
	global_load_dword v128, v[0:1], off
	global_load_dword v157, v[2:3], off
	global_load_dword v158, v[4:5], off
	global_load_dword v159, v[6:7], off
	global_load_dword v160, v[8:9], off
	global_load_dword v161, v[10:11], off
	global_load_dword v162, v[12:13], off
	global_load_dword v163, v[14:15], off
	v_add_co_u32_e32 v2, vcc, s3, v0
	s_mov_b32 s3, 0x64000
	s_nop 0
	v_addc_co_u32_e32 v3, vcc, 0, v1, vcc
	v_add_co_u32_e32 v4, vcc, s57, v0
	s_lshl_b32 s48, s28, 7
	s_nop 0
	v_addc_co_u32_e32 v5, vcc, 0, v1, vcc
	v_add_co_u32_e32 v6, vcc, s3, v0
	s_mov_b32 s3, 0x6e000
	s_nop 0
	v_addc_co_u32_e32 v7, vcc, 0, v1, vcc
	v_add_co_u32_e32 v8, vcc, s3, v0
	s_mov_b32 s3, 0x82000
	s_nop 0
	v_addc_co_u32_e32 v9, vcc, 0, v1, vcc
	v_add_co_u32_e32 v10, vcc, s62, v0
	s_mov_b32 s24, -2
	s_nop 0
	v_addc_co_u32_e32 v11, vcc, 0, v1, vcc
	v_add_co_u32_e32 v12, vcc, s3, v0
	s_mov_b32 s3, 0x8c000
	s_nop 0
	v_addc_co_u32_e32 v13, vcc, 0, v1, vcc
	v_add_co_u32_e32 v14, vcc, s3, v0
	s_nop 1
	v_addc_co_u32_e32 v15, vcc, 0, v1, vcc
	v_add_co_u32_e32 v0, vcc, s65, v0
	s_nop 1
	v_addc_co_u32_e32 v1, vcc, 0, v1, vcc
	global_load_dword v164, v[2:3], off
	global_load_dword v165, v[4:5], off
	global_load_dword v168, v[6:7], off
	global_load_dword v175, v[8:9], off
	global_load_dword v179, v[10:11], off
	global_load_dword v183, v[12:13], off
	global_load_dword v190, v[14:15], off
	global_load_dword v191, v[0:1], off
	v_add_u32_e32 v0, s2, v130
	v_ashrrev_i32_e32 v1, 31, v0
	v_lshlrev_b64 v[0:1], 11, v[0:1]
	v_lshl_add_u64 v[138:139], v[132:133], 0, v[0:1]
	v_add_u32_e32 v0, s48, v130
	v_ashrrev_i32_e32 v1, 31, v0
	v_lshlrev_b64 v[0:1], 11, v[0:1]
	v_lshl_add_u64 v[140:141], v[134:135], 0, v[0:1]
	v_add_co_u32_e32 v0, vcc, s11, v138
	s_nop 1
	v_addc_co_u32_e32 v1, vcc, 0, v139, vcc
	v_add_co_u32_e32 v2, vcc, s33, v138
	s_nop 1
	v_addc_co_u32_e32 v3, vcc, 0, v139, vcc
	global_load_dwordx4 v[100:103], v[0:1], off offset:128
	global_load_dwordx4 v[104:107], v[2:3], off offset:128
	v_add_co_u32_e32 v0, vcc, 0x30000, v138
	global_load_dwordx4 v[96:99], v[138:139], off offset:128
	global_load_dwordx4 v[108:111], v[140:141], off offset:128
	v_addc_co_u32_e32 v1, vcc, 0, v139, vcc
	v_add_co_u32_e32 v2, vcc, s11, v140
	s_nop 1
	v_addc_co_u32_e32 v3, vcc, 0, v141, vcc
	global_load_dwordx4 v[112:115], v[0:1], off offset:128
	global_load_dwordx4 v[116:119], v[2:3], off offset:128
	v_add_co_u32_e32 v0, vcc, 0x20000, v140
	s_nop 1
	v_addc_co_u32_e32 v1, vcc, 0, v141, vcc
	v_add_co_u32_e32 v2, vcc, 0x30000, v140
	s_nop 1
	v_addc_co_u32_e32 v3, vcc, 0, v141, vcc
	global_load_dwordx4 v[120:123], v[0:1], off offset:128
	global_load_dwordx4 v[124:127], v[2:3], off offset:128
	v_mov_b32_e32 v0, 0
	v_mov_b32_e32 v1, v0
	v_mov_b32_e32 v2, v0
	v_mov_b32_e32 v3, v0
	v_mov_b32_e32 v4, v0
	v_mov_b32_e32 v5, v0
	v_mov_b32_e32 v6, v0
	v_mov_b32_e32 v7, v0
	v_mov_b32_e32 v8, v0
	v_mov_b32_e32 v9, v0
	v_mov_b32_e32 v10, v0
	v_mov_b32_e32 v11, v0
	v_mov_b32_e32 v12, v0
	v_mov_b32_e32 v13, v0
	v_mov_b32_e32 v14, v0
	v_mov_b32_e32 v15, v0
	s_waitcnt vmcnt(41)
	v_mov_b32_e32 v24, v0
	v_mov_b32_e32 v25, v0
	v_mov_b32_e32 v26, v0
	v_mov_b32_e32 v27, v0
	s_waitcnt vmcnt(40)
	v_mov_b32_e32 v52, v0
	v_mov_b32_e32 v53, v0
	v_mov_b32_e32 v54, v0
	v_mov_b32_e32 v55, v0
	v_mov_b32_e32 v56, v0
	v_mov_b32_e32 v57, v0
	v_mov_b32_e32 v58, v0
	v_mov_b32_e32 v59, v0
	v_mov_b32_e32 v60, v0
	v_mov_b32_e32 v61, v0
	v_mov_b32_e32 v62, v0
	v_mov_b32_e32 v63, v0
	v_mov_b32_e32 v64, v0
	v_mov_b32_e32 v65, v0
	v_mov_b32_e32 v66, v0
	v_mov_b32_e32 v67, v0
	v_mov_b32_e32 v68, v0
	v_mov_b32_e32 v69, v0
	v_mov_b32_e32 v70, v0
	v_mov_b32_e32 v71, v0
	v_mov_b32_e32 v72, v0
	v_mov_b32_e32 v73, v0
	v_mov_b32_e32 v74, v0
	v_mov_b32_e32 v75, v0
	v_mov_b32_e32 v76, v0
	v_mov_b32_e32 v77, v0
	v_mov_b32_e32 v78, v0
	v_mov_b32_e32 v79, v0
	v_mov_b32_e32 v80, v0
	v_mov_b32_e32 v81, v0
	v_mov_b32_e32 v82, v0
	v_mov_b32_e32 v83, v0
	v_mov_b32_e32 v84, v0
	v_mov_b32_e32 v85, v0
	v_mov_b32_e32 v86, v0
	v_mov_b32_e32 v87, v0
	v_mov_b32_e32 v88, v0
	v_mov_b32_e32 v89, v0
	v_mov_b32_e32 v90, v0
	v_mov_b32_e32 v91, v0
	v_mov_b32_e32 v92, v0
	v_mov_b32_e32 v93, v0
	v_mov_b32_e32 v94, v0
	v_mov_b32_e32 v95, v0
	s_waitcnt vmcnt(29)
	ds_write_b128 v156, v[20:23]
	ds_write_b128 v156, v[16:19] offset:4096
	ds_write_b128 v156, v[28:31] offset:8192
	s_waitcnt vmcnt(27)
	ds_write_b128 v156, v[36:39] offset:12288
	ds_write_b128 v156, v[32:35] offset:16384
	s_waitcnt vmcnt(26)
	ds_write_b128 v156, v[40:43] offset:20480
	s_waitcnt vmcnt(25)
	ds_write_b128 v156, v[44:47] offset:24576
	s_waitcnt vmcnt(24)
	ds_write_b128 v156, v[48:51] offset:28672
	s_waitcnt lgkmcnt(0)
	s_barrier

.LBB0_664:
	s_and_b64 vcc, exec, s[2:3]
	s_cbranch_vccz .LBB0_759
	v_mov_b32_e32 v109, v166
	s_movk_i32 s2, 0x70
	v_ashrrev_i32_e32 v106, 3, v109
	v_lshlrev_b32_e32 v3, 4, v109
	v_lshlrev_b32_e32 v2, 7, v106
	v_xor_b32_e32 v4, v3, v109
	v_and_b32_e32 v0, 15, v109
	s_waitcnt lgkmcnt(0)
	v_ashrrev_i32_e32 v1, 1, v109
	s_waitcnt vmcnt(11)
	v_and_or_b32 v35, v4, s2, v2
	s_movk_i32 s2, 0xffc0
	v_bfe_u32 v108, v109, 6, 1
	v_and_or_b32 v120, v1, s2, v0
	v_lshlrev_b32_e32 v0, 7, v0
	v_readlane_b32 s16, v251, 54
	v_lshl_or_b32 v36, v108, 13, v0
	v_readlane_b32 s2, v250, 21
	v_add_u32_e32 v0, s16, v106
	v_ashrrev_i32_e32 v1, 31, v0
	s_waitcnt vmcnt(10)
	v_lshlrev_b64 v[28:29], 11, v[0:1]
	v_readlane_b32 s3, v250, 22
	v_and_b32_e32 v128, 0x70, v3
	v_readlane_b32 s21, v251, 40
	v_lshl_add_u64 v[0:1], s[2:3], 0, v[28:29]
	v_lshl_add_u64 v[8:9], v[0:1], 0, v[128:129]
	v_add_u32_e32 v0, s21, v106
	v_ashrrev_i32_e32 v1, 31, v0
	v_lshlrev_b64 v[30:31], 11, v[0:1]
	v_lshl_add_u64 v[0:1], s[38:39], 0, v[30:31]
	s_waitcnt vmcnt(9)
	v_lshl_add_u64 v[24:25], v[0:1], 0, v[128:129]
	v_add_co_u32_e32 v0, vcc, s11, v8
	v_lshl_add_u64 v[98:99], s[2:3], 0, v[128:129]
	s_nop 0
	v_addc_co_u32_e32 v1, vcc, 0, v9, vcc
	v_add_co_u32_e32 v4, vcc, s33, v8
	v_lshl_add_u64 v[100:101], s[38:39], 0, v[128:129]
	s_nop 0
	v_addc_co_u32_e32 v5, vcc, 0, v9, vcc
	v_add_co_u32_e32 v16, vcc, s59, v8
	global_load_dwordx4 v[0:3], v[0:1], off
	s_nop 0
	global_load_dwordx4 v[4:7], v[4:5], off
	v_addc_co_u32_e32 v17, vcc, 0, v9, vcc
	s_waitcnt vmcnt(10)
	v_add_co_u32_e32 v20, vcc, s11, v24
	global_load_dwordx4 v[8:11], v[8:9], off
	s_nop 0
	global_load_dwordx4 v[12:15], v[24:25], off
	v_addc_co_u32_e32 v21, vcc, 0, v25, vcc
	v_add_co_u32_e32 v26, vcc, s33, v24
	global_load_dwordx4 v[16:19], v[16:17], off
	s_nop 0
	global_load_dwordx4 v[20:23], v[20:21], off
	v_addc_co_u32_e32 v27, vcc, 0, v25, vcc
	v_add_co_u32_e32 v32, vcc, s59, v24
	v_readlane_b32 s17, v251, 55
	s_nop 0
	v_addc_co_u32_e32 v33, vcc, 0, v25, vcc
	global_load_dwordx4 v[24:27], v[26:27], off
	s_nop 0
	global_load_dwordx4 v[48:51], v[32:33], off
	v_and_b32_e32 v32, 0x7f, v109
	v_lshlrev_b32_e32 v128, 2, v32
	v_lshl_add_u64 v[96:97], s[26:27], 0, v[128:129]
	v_lshrrev_b32_e32 v34, 4, v109
	v_bfe_u32 v64, v109, 1, 3
	v_lshl_add_u64 v[32:33], s[16:17], 2, v[96:97]
	s_mov_b32 s2, 0xa000
	v_bitop3_b32 v65, v64, v34, 3 bitop3:0x78
	v_add_co_u32_e32 v34, vcc, s2, v32
	v_add_u32_e32 v121, 0, v35
	s_nop 0
	v_addc_co_u32_e32 v35, vcc, 0, v33, vcc
	s_mov_b32 s2, 0x14000
	v_add_u32_e32 v111, 0, v36
	v_add_co_u32_e32 v36, vcc, s2, v32
	s_mov_b32 s2, 0x28000
	s_nop 0
	v_addc_co_u32_e32 v37, vcc, 0, v33, vcc
	v_add_co_u32_e32 v38, vcc, s12, v32
	s_nop 1
	v_addc_co_u32_e32 v39, vcc, 0, v33, vcc
	v_add_co_u32_e32 v40, vcc, s2, v32
	s_mov_b32 s2, 0x32000
	s_nop 0
	v_addc_co_u32_e32 v41, vcc, 0, v33, vcc
	v_add_co_u32_e32 v42, vcc, s2, v32
	s_mov_b32 s2, 0x46000
	s_nop 0
	v_addc_co_u32_e32 v43, vcc, 0, v33, vcc
	v_add_co_u32_e32 v44, vcc, s63, v32
	s_nop 0
	s_nop 0
	v_addc_co_u32_e32 v45, vcc, 0, v33, vcc
	v_add_co_u32_e32 v46, vcc, s2, v32
	s_mov_b32 s2, 0x50000
	s_nop 0
	v_addc_co_u32_e32 v47, vcc, 0, v33, vcc
	global_load_dword v112, v[32:33], off
	global_load_dword v113, v[34:35], off
	global_load_dword v114, v[36:37], off
	global_load_dword v115, v[38:39], off
	global_load_dword v116, v[40:41], off
	global_load_dword v117, v[42:43], off
	global_load_dword v118, v[44:45], off
	global_load_dword v119, v[46:47], off
	v_add_co_u32_e32 v34, vcc, s2, v32
	s_mov_b32 s2, 0x64000
	s_nop 0
	v_addc_co_u32_e32 v35, vcc, 0, v33, vcc
	v_add_co_u32_e32 v36, vcc, s57, v32
	v_lshl_add_u64 v[102:103], v[98:99], 0, v[28:29]
	s_nop 0
	v_addc_co_u32_e32 v37, vcc, 0, v33, vcc
	v_add_co_u32_e32 v38, vcc, s2, v32
	s_mov_b32 s2, 0x6e000
	s_nop 0
	v_addc_co_u32_e32 v39, vcc, 0, v33, vcc
	v_add_co_u32_e32 v40, vcc, s2, v32
	s_mov_b32 s2, 0x82000
	s_nop 0
	v_addc_co_u32_e32 v41, vcc, 0, v33, vcc
	v_add_co_u32_e32 v42, vcc, s62, v32
	v_lshl_add_u64 v[104:105], v[100:101], 0, v[30:31]
	s_nop 0
	v_addc_co_u32_e32 v43, vcc, 0, v33, vcc
	v_add_co_u32_e32 v44, vcc, s2, v32
	s_mov_b32 s2, 0x8c000
	s_nop 0
	v_addc_co_u32_e32 v45, vcc, 0, v33, vcc
	v_add_co_u32_e32 v46, vcc, s2, v32
	v_bfe_u32 v107, v109, 4, 2
	s_nop 0
	v_addc_co_u32_e32 v47, vcc, 0, v33, vcc
	v_add_co_u32_e32 v32, vcc, s65, v32
	v_bitop3_b32 v64, v107, v64, 4 bitop3:0x36
	s_nop 0
	v_addc_co_u32_e32 v33, vcc, 0, v33, vcc
	v_add_co_u32_e32 v28, vcc, s11, v102
	global_load_dword v127, v[34:35], off
	global_load_dword v128, v[36:37], off
	global_load_dword v130, v[38:39], off
	global_load_dword v132, v[40:41], off
	global_load_dword v133, v[42:43], off
	global_load_dword v134, v[44:45], off
	global_load_dword v135, v[46:47], off
	global_load_dword v136, v[32:33], off
	v_addc_co_u32_e32 v29, vcc, 0, v103, vcc
	v_add_co_u32_e32 v30, vcc, s33, v102
	v_lshl_add_u32 v110, v120, 7, 0
	s_nop 0
	v_addc_co_u32_e32 v31, vcc, 0, v103, vcc
	v_add_co_u32_e32 v44, vcc, 0x30000, v102
	global_load_dwordx4 v[32:35], v[28:29], off offset:128
	global_load_dwordx4 v[36:39], v[30:31], off offset:128
	v_addc_co_u32_e32 v45, vcc, 0, v103, vcc
	v_add_co_u32_e32 v52, vcc, s11, v104
	global_load_dwordx4 v[28:31], v[102:103], off offset:128
	global_load_dwordx4 v[40:43], v[104:105], off offset:128
	v_addc_co_u32_e32 v53, vcc, 0, v105, vcc
	v_add_co_u32_e32 v56, vcc, 0x20000, v104
	global_load_dwordx4 v[44:47], v[44:45], off offset:128
	s_nop 0
	global_load_dwordx4 v[52:55], v[52:53], off offset:128
	v_addc_co_u32_e32 v57, vcc, 0, v105, vcc
	v_add_co_u32_e32 v60, vcc, 0x30000, v104
	v_lshlrev_b32_e32 v126, 4, v65
	s_nop 0
	v_addc_co_u32_e32 v61, vcc, 0, v105, vcc
	global_load_dwordx4 v[56:59], v[56:57], off offset:128
	s_nop 0
	global_load_dwordx4 v[60:63], v[60:61], off offset:128
	s_waitcnt vmcnt(29)
	ds_write_b128 v121, v[8:11]
	ds_write_b128 v121, v[0:3] offset:4096
	ds_write_b128 v121, v[4:7] offset:8192
	s_waitcnt vmcnt(27)
	ds_write_b128 v121, v[16:19] offset:12288
	ds_write_b128 v121, v[12:15] offset:16384
	s_waitcnt vmcnt(26)
	ds_write_b128 v121, v[20:23] offset:20480
	s_waitcnt vmcnt(25)
	ds_write_b128 v121, v[24:27] offset:24576
	s_waitcnt vmcnt(24)
	ds_write_b128 v121, v[48:51] offset:28672
	v_mov_b32_e32 v0, 0
	v_lshlrev_b32_e32 v137, 4, v64
	s_mov_b32 s3, -2
	v_mov_b32_e32 v1, v0
	v_mov_b32_e32 v2, v0
	v_mov_b32_e32 v3, v0
	v_mov_b32_e32 v4, v0
	v_mov_b32_e32 v5, v0
	v_mov_b32_e32 v6, v0
	v_mov_b32_e32 v7, v0
	v_mov_b32_e32 v8, v0
	v_mov_b32_e32 v9, v0
	v_mov_b32_e32 v10, v0
	v_mov_b32_e32 v11, v0
	v_mov_b32_e32 v12, v0
	v_mov_b32_e32 v13, v0
	v_mov_b32_e32 v14, v0
	v_mov_b32_e32 v15, v0
	v_mov_b32_e32 v16, v0
	v_mov_b32_e32 v17, v0
	v_mov_b32_e32 v18, v0
	v_mov_b32_e32 v19, v0
	v_mov_b32_e32 v20, v0
	v_mov_b32_e32 v21, v0
	v_mov_b32_e32 v22, v0
	v_mov_b32_e32 v23, v0
	v_mov_b32_e32 v24, v0
	v_mov_b32_e32 v25, v0
	v_mov_b32_e32 v26, v0
	v_mov_b32_e32 v27, v0
	v_mov_b32_e32 v48, v0
	v_mov_b32_e32 v49, v0
	v_mov_b32_e32 v50, v0
	v_mov_b32_e32 v51, v0
	v_mov_b32_e32 v64, v0
	v_mov_b32_e32 v65, v0
	v_mov_b32_e32 v66, v0
	v_mov_b32_e32 v67, v0
	v_mov_b32_e32 v68, v0
	v_mov_b32_e32 v69, v0
	v_mov_b32_e32 v70, v0
	v_mov_b32_e32 v71, v0
	v_mov_b32_e32 v72, v0
	v_mov_b32_e32 v73, v0
	v_mov_b32_e32 v74, v0
	v_mov_b32_e32 v75, v0
	v_mov_b32_e32 v76, v0
	v_mov_b32_e32 v77, v0
	v_mov_b32_e32 v78, v0
	v_mov_b32_e32 v79, v0
	v_mov_b32_e32 v80, v0
	v_mov_b32_e32 v81, v0
	v_mov_b32_e32 v82, v0
	v_mov_b32_e32 v83, v0
	v_mov_b32_e32 v84, v0
	v_mov_b32_e32 v85, v0
	v_mov_b32_e32 v86, v0
	v_mov_b32_e32 v87, v0
	v_mov_b32_e32 v88, v0
	v_mov_b32_e32 v89, v0
	v_mov_b32_e32 v90, v0
	v_mov_b32_e32 v91, v0
	v_mov_b32_e32 v92, v0
	v_mov_b32_e32 v93, v0
	v_mov_b32_e32 v94, v0
	v_mov_b32_e32 v95, v0
	s_waitcnt lgkmcnt(0)
	s_barrier

.LBB0_701:
	s_or_b64 exec, exec, s[2:3]
	s_nop 0
	v_lshl_add_u64 v[0:1], s[16:17], 2, v[96:97]
	v_add_co_u32_e32 v2, vcc, 0xa000, v0
	s_nop 1
	v_addc_co_u32_e32 v3, vcc, 0, v1, vcc
	v_add_co_u32_e32 v4, vcc, 0x14000, v0
	s_nop 0
	s_nop 0
	v_addc_co_u32_e32 v5, vcc, 0, v1, vcc
	v_add_co_u32_e32 v6, vcc, 0x1e000, v0
	s_nop 1
	v_addc_co_u32_e32 v7, vcc, 0, v1, vcc
	v_add_co_u32_e32 v8, vcc, 0x28000, v0
	s_mov_b32 s3, -2
	s_nop 0
	v_addc_co_u32_e32 v9, vcc, 0, v1, vcc
	v_add_co_u32_e32 v10, vcc, 0x32000, v0
	s_nop 1
	v_addc_co_u32_e32 v11, vcc, 0, v1, vcc
	v_add_co_u32_e32 v12, vcc, 0x3c000, v0
	s_nop 1
	v_addc_co_u32_e32 v13, vcc, 0, v1, vcc
	v_add_co_u32_e32 v14, vcc, 0x46000, v0
	s_nop 1
	v_addc_co_u32_e32 v15, vcc, 0, v1, vcc
	global_load_dword v96, v[0:1], off
	global_load_dword v97, v[2:3], off
	global_load_dword v108, v[4:5], off
	global_load_dword v109, v[6:7], off
	global_load_dword v110, v[8:9], off
	global_load_dword v111, v[10:11], off
	global_load_dword v118, v[12:13], off
	global_load_dword v119, v[14:15], off
	v_add_co_u32_e32 v2, vcc, 0x50000, v0
	s_nop 1
	v_addc_co_u32_e32 v3, vcc, 0, v1, vcc
	v_add_co_u32_e32 v4, vcc, 0x5a000, v0
	s_nop 1
	v_addc_co_u32_e32 v5, vcc, 0, v1, vcc
	v_add_co_u32_e32 v6, vcc, 0x64000, v0
	s_nop 1
	v_addc_co_u32_e32 v7, vcc, 0, v1, vcc
	v_add_co_u32_e32 v8, vcc, 0x6e000, v0
	s_nop 1
	v_addc_co_u32_e32 v9, vcc, 0, v1, vcc
	v_add_co_u32_e32 v10, vcc, 0x78000, v0
	s_nop 1
	v_addc_co_u32_e32 v11, vcc, 0, v1, vcc
	v_add_co_u32_e32 v12, vcc, 0x82000, v0
	s_nop 1
	v_addc_co_u32_e32 v13, vcc, 0, v1, vcc
	v_add_co_u32_e32 v14, vcc, 0x8c000, v0
	s_nop 1
	v_addc_co_u32_e32 v15, vcc, 0, v1, vcc
	v_add_co_u32_e32 v0, vcc, 0x96000, v0
	s_nop 1
	v_addc_co_u32_e32 v1, vcc, 0, v1, vcc
	global_load_dword v128, v[2:3], off
	global_load_dword v132, v[4:5], off
	global_load_dword v133, v[6:7], off
	global_load_dword v134, v[8:9], off
	global_load_dword v135, v[10:11], off
	global_load_dword v136, v[12:13], off
	global_load_dword v137, v[14:15], off
	global_load_dword v138, v[0:1], off
	global_load_dwordx4 v[68:71], v[102:103], off offset:128
	global_load_dwordx4 v[72:75], v[104:105], off offset:128
	v_add_co_u32_e32 v0, vcc, 0x30000, v98
	s_nop 1
	v_addc_co_u32_e32 v1, vcc, 0, v99, vcc
	global_load_dwordx4 v[64:67], v[98:99], off offset:128
	global_load_dwordx4 v[76:79], v[100:101], off offset:128
	global_load_dwordx4 v[80:83], v[0:1], off offset:128
	global_load_dwordx4 v[84:87], v[106:107], off offset:128
	v_add_co_u32_e32 v0, vcc, 0x20000, v100
	s_nop 1
	v_addc_co_u32_e32 v1, vcc, 0, v101, vcc
	v_add_co_u32_e32 v2, vcc, 0x30000, v100
	s_nop 1
	v_addc_co_u32_e32 v3, vcc, 0, v101, vcc
	global_load_dwordx4 v[88:91], v[0:1], off offset:128
	global_load_dwordx4 v[92:95], v[2:3], off offset:128
	v_mov_b32_e32 v0, 0
	ds_write_b128 v121, v[28:31]
	ds_write_b128 v121, v[32:35] offset:4096
	ds_write_b128 v121, v[36:39] offset:8192
	ds_write_b128 v121, v[40:43] offset:12288
	ds_write_b128 v121, v[44:47] offset:16384
	ds_write_b128 v121, v[52:55] offset:20480
	ds_write_b128 v121, v[56:59] offset:24576
	ds_write_b128 v121, v[60:63] offset:28672
	v_mov_b32_e32 v1, v0
	v_mov_b32_e32 v2, v0
	v_mov_b32_e32 v3, v0
	v_mov_b32_e32 v4, v0
	v_mov_b32_e32 v5, v0
	v_mov_b32_e32 v6, v0
	v_mov_b32_e32 v7, v0
	v_mov_b32_e32 v8, v0
	v_mov_b32_e32 v9, v0
	v_mov_b32_e32 v10, v0
	v_mov_b32_e32 v11, v0
	v_mov_b32_e32 v12, v0
	v_mov_b32_e32 v13, v0
	v_mov_b32_e32 v14, v0
	v_mov_b32_e32 v15, v0
	v_mov_b32_e32 v16, v0
	v_mov_b32_e32 v17, v0
	v_mov_b32_e32 v18, v0
	v_mov_b32_e32 v19, v0
	v_mov_b32_e32 v20, v0
	v_mov_b32_e32 v21, v0
	v_mov_b32_e32 v22, v0
	v_mov_b32_e32 v23, v0
	v_mov_b32_e32 v24, v0
	v_mov_b32_e32 v25, v0
	v_mov_b32_e32 v26, v0
	v_mov_b32_e32 v27, v0
	v_mov_b32_e32 v28, v0
	v_mov_b32_e32 v29, v0
	v_mov_b32_e32 v30, v0
	v_mov_b32_e32 v31, v0
	v_mov_b32_e32 v32, v0
	v_mov_b32_e32 v33, v0
	v_mov_b32_e32 v34, v0
	v_mov_b32_e32 v35, v0
	v_mov_b32_e32 v36, v0
	v_mov_b32_e32 v37, v0
	v_mov_b32_e32 v38, v0
	v_mov_b32_e32 v39, v0
	v_mov_b32_e32 v40, v0
	v_mov_b32_e32 v41, v0
	v_mov_b32_e32 v42, v0
	v_mov_b32_e32 v43, v0
	v_mov_b32_e32 v44, v0
	v_mov_b32_e32 v45, v0
	v_mov_b32_e32 v46, v0
	v_mov_b32_e32 v47, v0
	v_mov_b32_e32 v48, v0
	v_mov_b32_e32 v49, v0
	v_mov_b32_e32 v50, v0
	v_mov_b32_e32 v51, v0
	v_mov_b32_e32 v52, v0
	v_mov_b32_e32 v53, v0
	v_mov_b32_e32 v54, v0
	v_mov_b32_e32 v55, v0
	v_mov_b32_e32 v56, v0
	v_mov_b32_e32 v57, v0
	v_mov_b32_e32 v58, v0
	v_mov_b32_e32 v59, v0
	v_mov_b32_e32 v60, v0
	v_mov_b32_e32 v61, v0
	v_mov_b32_e32 v62, v0
	v_mov_b32_e32 v63, v0
	s_waitcnt lgkmcnt(0)
	s_barrier

.LBB0_737:
	s_or_b64 exec, exec, s[2:3]
	v_readlane_b32 s2, v251, 48
	v_readlane_b32 s3, v251, 49
	s_andn2_b64 vcc, exec, s[2:3]
	s_cbranch_vccnz .LBB0_759
	v_mov_b32_e32 v85, v166
	v_readlane_b32 s16, v251, 50
	v_ashrrev_i32_e32 v50, 3, v85
	v_readlane_b32 s2, v250, 21
	v_add_u32_e32 v0, s16, v50
	v_ashrrev_i32_e32 v1, 31, v0
	v_lshlrev_b32_e32 v51, 4, v85
	v_lshlrev_b64 v[0:1], 11, v[0:1]
	v_readlane_b32 s3, v250, 22
	v_and_b32_e32 v128, 0x70, v51
	v_and_b32_e32 v20, 0x7f, v85
	v_lshl_add_u64 v[0:1], s[2:3], 0, v[0:1]
	v_lshl_add_u64 v[80:81], v[0:1], 0, v[128:129]
	v_readlane_b32 s2, v251, 51
	v_add_co_u32_e32 v12, vcc, s11, v80
	s_nop 0
	v_add_u32_e32 v0, s2, v50
	v_addc_co_u32_e32 v13, vcc, 0, v81, vcc
	v_ashrrev_i32_e32 v1, 31, v0
	v_add_co_u32_e32 v14, vcc, s33, v80
	v_lshlrev_b64 v[0:1], 11, v[0:1]
	s_nop 0
	v_addc_co_u32_e32 v15, vcc, 0, v81, vcc
	v_lshl_add_u64 v[0:1], s[38:39], 0, v[0:1]
	v_add_co_u32_e32 v24, vcc, s59, v80
	s_lshl_b32 s2, s16, 2
	v_lshl_add_u64 v[82:83], v[0:1], 0, v[128:129]
	v_addc_co_u32_e32 v25, vcc, 0, v81, vcc
	s_add_u32 s2, s26, s2
	v_add_co_u32_e32 v48, vcc, s11, v82
	s_addc_u32 s3, s27, 0
	v_lshlrev_b32_e32 v128, 2, v20
	v_addc_co_u32_e32 v49, vcc, 0, v83, vcc
	v_lshl_add_u64 v[20:21], s[2:3], 0, v[128:129]
	s_mov_b32 s16, 0xa000
	v_add_co_u32_e32 v22, vcc, s16, v20
	s_mov_b32 s16, 0x14000
	s_nop 0
	v_addc_co_u32_e32 v23, vcc, 0, v21, vcc
	v_add_co_u32_e32 v26, vcc, s16, v20
	s_mov_b32 s16, 0x28000
	s_nop 0
	v_addc_co_u32_e32 v27, vcc, 0, v21, vcc
	v_add_co_u32_e32 v28, vcc, s12, v20
	global_load_dwordx4 v[0:3], v[12:13], off
	global_load_dwordx4 v[4:7], v[14:15], off
	v_addc_co_u32_e32 v29, vcc, 0, v21, vcc
	v_add_co_u32_e32 v30, vcc, s16, v20
	s_mov_b32 s16, 0x32000
	s_nop 0
	v_addc_co_u32_e32 v31, vcc, 0, v21, vcc
	v_add_co_u32_e32 v32, vcc, s16, v20
	s_mov_b32 s16, 0x46000
	s_nop 0
	v_addc_co_u32_e32 v33, vcc, 0, v21, vcc
	v_add_co_u32_e32 v34, vcc, s63, v20
	global_load_dwordx4 v[8:11], v[80:81], off
	global_load_dwordx4 v[16:19], v[82:83], off
	v_addc_co_u32_e32 v35, vcc, 0, v21, vcc
	v_add_co_u32_e32 v36, vcc, s16, v20
	s_mov_b32 s16, 0x50000
	s_nop 0
	v_addc_co_u32_e32 v37, vcc, 0, v21, vcc
	v_add_co_u32_e32 v38, vcc, s16, v20
	global_load_dwordx4 v[40:43], v[24:25], off
	global_load_dwordx4 v[44:47], v[48:49], off
	v_addc_co_u32_e32 v39, vcc, 0, v21, vcc
	global_load_dword v86, v[22:23], off
	global_load_dword v87, v[26:27], off
	global_load_dword v88, v[28:29], off
	global_load_dword v89, v[30:31], off
	global_load_dword v90, v[32:33], off
	global_load_dword v91, v[34:35], off
	global_load_dword v92, v[36:37], off
	global_load_dword v93, v[38:39], off
	v_add_co_u32_e32 v22, vcc, s57, v20
	s_mov_b32 s16, 0x64000
	s_nop 0
	v_addc_co_u32_e32 v23, vcc, 0, v21, vcc
	v_add_co_u32_e32 v26, vcc, s16, v20
	s_mov_b32 s16, 0x6e000
	s_nop 0
	v_addc_co_u32_e32 v27, vcc, 0, v21, vcc
	v_add_co_u32_e32 v28, vcc, s16, v20
	s_mov_b32 s16, 0x82000
	s_nop 0
	v_addc_co_u32_e32 v29, vcc, 0, v21, vcc
	v_add_co_u32_e32 v30, vcc, s62, v20
	v_lshlrev_b32_e32 v50, 7, v50
	s_nop 0
	v_addc_co_u32_e32 v31, vcc, 0, v21, vcc
	v_add_co_u32_e32 v32, vcc, s16, v20
	s_mov_b32 s16, 0x8c000
	s_nop 0
	v_addc_co_u32_e32 v33, vcc, 0, v21, vcc
	v_add_co_u32_e32 v34, vcc, s16, v20
	v_xor_b32_e32 v51, v51, v85
	s_nop 0
	v_addc_co_u32_e32 v35, vcc, 0, v21, vcc
	v_add_co_u32_e32 v20, vcc, s65, v20
	v_bfe_u32 v94, v85, 4, 2
	s_nop 0
	v_addc_co_u32_e32 v21, vcc, 0, v21, vcc
	global_load_dword v102, v128, s[2:3]
	global_load_dword v95, v[22:23], off
	global_load_dword v96, v[26:27], off
	global_load_dword v97, v[28:29], off
	global_load_dword v98, v[30:31], off
	global_load_dword v99, v[32:33], off
	global_load_dword v100, v[34:35], off
	global_load_dword v101, v[20:21], off
	s_nop 0
	global_load_dwordx4 v[32:35], v[12:13], off offset:128
	global_load_dwordx4 v[28:31], v[14:15], off offset:128
	global_load_dwordx4 v[36:39], v[80:81], off offset:128
	global_load_dwordx4 v[20:23], v[82:83], off offset:128
	s_nop 0
	global_load_dwordx4 v[24:27], v[24:25], off offset:128
	s_nop 0
	global_load_dwordx4 v[12:15], v[48:49], off offset:128
	s_movk_i32 s2, 0x70
	v_and_or_b32 v50, v51, s2, v50
	v_lshrrev_b32_e32 v49, 4, v85
	v_bfe_u32 v51, v85, 1, 3
	v_add_u32_e32 v103, 0, v50
	s_waitcnt vmcnt(25)
	ds_write_b128 v103, v[8:11]
	ds_write_b128 v103, v[0:3] offset:4096
	ds_write_b128 v103, v[4:7] offset:8192
	s_waitcnt vmcnt(23)
	ds_write_b128 v103, v[40:43] offset:12288
	ds_write_b128 v103, v[16:19] offset:16384
	s_waitcnt vmcnt(22)
	ds_write_b128 v103, v[44:47] offset:20480
	v_bitop3_b32 v0, v51, v49, 3 bitop3:0x78
	v_and_b32_e32 v48, 15, v85
	v_ashrrev_i32_e32 v52, 1, v85
	s_movk_i32 s2, 0xffe0
	v_lshlrev_b32_e32 v106, 4, v0
	v_bitop3_b32 v0, v94, v51, 4 bitop3:0x36
	v_and_or_b32 v84, v52, s2, v48
	v_lshlrev_b32_e32 v107, 4, v0
	v_mov_b32_e32 v0, 0
	v_lshl_add_u32 v104, v84, 7, 0
	v_lshl_add_u32 v105, v48, 7, 0
	s_mov_b32 s3, -2
	v_mov_b32_e32 v1, v0
	v_mov_b32_e32 v2, v0
	v_mov_b32_e32 v3, v0
	v_mov_b32_e32 v4, v0
	v_mov_b32_e32 v5, v0
	v_mov_b32_e32 v6, v0
	v_mov_b32_e32 v7, v0
	v_mov_b32_e32 v8, v0
	v_mov_b32_e32 v9, v0
	v_mov_b32_e32 v10, v0
	v_mov_b32_e32 v11, v0
	v_mov_b32_e32 v16, v0
	v_mov_b32_e32 v17, v0
	v_mov_b32_e32 v18, v0
	v_mov_b32_e32 v19, v0
	v_mov_b32_e32 v40, v0
	v_mov_b32_e32 v41, v0
	v_mov_b32_e32 v42, v0
	v_mov_b32_e32 v43, v0
	v_mov_b32_e32 v44, v0
	v_mov_b32_e32 v45, v0
	v_mov_b32_e32 v46, v0
	v_mov_b32_e32 v47, v0
	v_mov_b32_e32 v48, v0
	v_mov_b32_e32 v49, v0
	v_mov_b32_e32 v50, v0
	v_mov_b32_e32 v51, v0
	v_mov_b32_e32 v72, v0
	v_mov_b32_e32 v73, v0
	v_mov_b32_e32 v74, v0
	v_mov_b32_e32 v75, v0
	s_waitcnt lgkmcnt(0)
	s_barrier
